# v63 + removed 20 redundant s_waitcnt lgkmcnt(0) at the MFMA segment heads (already waited before the barrier)
# baseline (speedup 1.0000x reference)
; #define PG8_STAGE(bufoff, gbase, voff) do { _Pragma("unroll") for (int _i = 0; _i < 2; ++_i) \
;         __builtin_amdgcn_global_load_lds((const unsigned*)((const char*)(gbase) + (voff)[_i]), (PG8_LAS unsigned*)(lds + (bufoff) + ldsw + _i * 8192), 16, 0, 0); } while (0)
; #define PG8_LDA(dst, b, h) do { _Pragma("unroll") for (int m = 0; m < 4; ++m) _Pragma("unroll") for (int k = 0; k < 2; ++k) dst[m][k] = *(const PG8_LAS bf16x8*)(lds + PG8_SA(b, h) + aoff + m * 2048 + k * 1024); } while (0)
; #define PG8_LDB(dst, b, h) do { _Pragma("unroll") for (int n = 0; n < 2; ++n) _Pragma("unroll") for (int k = 0; k < 2; ++k) dst[n][k] = *(const PG8_LAS bf16x8*)(lds + PG8_SB(b, h) + boff + n * 2048 + k * 1024); } while (0)
; #define PG8_MMA(ai, bj, At, Bt) do { __builtin_amdgcn_s_setprio(1); _Pragma("unroll") for (int m = 0; m < 4; ++m) _Pragma("unroll") for (int n = 0; n < 2; ++n) _Pragma("unroll") for (int k = 0; k < 2; ++k) \
;         acc[ai][bj][m][n] = __builtin_amdgcn_mfma_f32_16x16x32_bf16(Bt[n][k], At[m][k], acc[ai][bj][m][n], 0, 0, 0); __builtin_amdgcn_s_setprio(0); } while (0)
; #define PG8_WAIT_V(n) asm volatile("s_waitcnt vmcnt(" #n ")" ::: "memory")
; #define PG8_BAR __builtin_amdgcn_s_barrier()
; template <class Epi, class Sched, bool ALIGN_EPI = false, bool SP2 = false>
; __device__ __forceinline__ void gemm_phase(PG8_LAS unsigned char* lds, const Gemm g, const Sched& S, const Epi& E) {
;     ...
;         for (int t = 0; t < nt; t += 2) {
;             const bool last = (t == nt - 2);
;             const char* a1 = cA + (size_t)(t + 1) * kstep;
;             const char* a2 = last ? nA : cA + (size_t)(t + 2) * kstep; const char* b2 = last ? nB : cB + (size_t)(t + 2) * kstep;
;             const char* a3 = a2 + kstep; const char* b3 = b2 + kstep;
;             if (last && has_next) S.a_ready(nxt);
;             if constexpr (SP2) {
;             PG8_LDB(B0, 0, 0); PG8_LDB(B1, 0, 1); PG8_SCHED; PG8_LDA(At, 0, 0); PG8_STAGE(PG8_SA(1, 1), a1 + hstep, voffA);
;             PG8_WAIT_V(8); PG8_WAIT_L(0); PG8_BAR; PG8_MMA(0, 0, At, B0); PG8_MMA(0, 1, At, B1); PG8_BAR; PG8_SCHED;
;             PG8_LDA(At, 0, 1); PG8_STAGE(PG8_SB(0, 0), b2, voffB); PG8_STAGE(PG8_SB(0, 1), b2 + hstep, voffB); PG8_STAGE(PG8_SA(0, 0), a2, voffA);
;             PG8_WAIT_V(8); PG8_WAIT_L(0); PG8_BAR; PG8_MMA(1, 0, At, B0); PG8_MMA(1, 1, At, B1); PG8_BAR; PG8_SCHED;
.LBB0_139:
	s_add_u32 s36, s30, 0xfff80080
	s_addc_u32 s37, s31, -1
	s_add_i32 s70, 0, 0x10000
	s_cmp_eq_u32 s69, 28
	s_cselect_b32 s39, s25, s37
	s_cselect_b32 s38, s45, s36
	v_add_u32_e32 v142, s70, v148
	s_cselect_b32 s37, s23, s68
	s_cselect_b32 s36, s66, s67
	s_add_i32 s75, 0, 0x14000
	ds_read_b128 v[152:155], v142
	ds_read_b128 v[166:169], v142 offset:1024
	ds_read_b128 v[170:173], v142 offset:2048
	ds_read_b128 v[174:177], v142 offset:3072
	v_add_u32_e32 v142, s75, v148
	ds_read_b128 v[178:181], v142
	ds_read_b128 v[182:185], v142 offset:1024
	ds_read_b128 v[186:189], v142 offset:2048
	ds_read_b128 v[190:193], v142 offset:3072
	s_add_u32 s98, s30, 0xfff80000
	s_addc_u32 s99, s31, -1
	s_mov_b32 m0, s57
	s_nop 0
	global_load_lds_dwordx4 v138, s[98:99]
	s_mov_b32 m0, s58
	s_nop 0
	global_load_lds_dwordx4 v140, s[98:99]
	s_add_i32 m0, s53, 0xc000
	ds_read_b128 v[200:203], v151
	ds_read_b128 v[204:207], v151 offset:1024
	ds_read_b128 v[208:211], v151 offset:2048
	ds_read_b128 v[212:215], v151 offset:3072
	ds_read_b128 v[216:219], v151 offset:4096
	ds_read_b128 v[220:223], v151 offset:5120
	ds_read_b128 v[224:227], v151 offset:6144
	ds_read_b128 v[228:231], v151 offset:7168
	global_load_lds_dwordx4 v138, s[30:31]
	s_add_i32 m0, s53, 0xe000
	s_nop 0
	global_load_lds_dwordx4 v140, s[30:31]
	s_waitcnt vmcnt(8)
	s_waitcnt lgkmcnt(0)
	s_barrier
	v_mfma_f32_16x16x32_bf16 v[126:129], v[152:155], v[200:203], v[126:129]
	v_mfma_f32_16x16x32_bf16 v[122:125], v[170:173], v[200:203], v[122:125]
	v_mfma_f32_16x16x32_bf16 v[110:113], v[152:155], v[208:211], v[110:113]
	v_mfma_f32_16x16x32_bf16 v[106:109], v[170:173], v[208:211], v[106:109]
	v_mfma_f32_16x16x32_bf16 v[94:97], v[152:155], v[216:219], v[94:97]
	v_mfma_f32_16x16x32_bf16 v[90:93], v[170:173], v[216:219], v[90:93]
	v_mfma_f32_16x16x32_bf16 v[78:81], v[152:155], v[224:227], v[78:81]
	v_mfma_f32_16x16x32_bf16 v[74:77], v[170:173], v[224:227], v[74:77]
	v_mfma_f32_16x16x32_bf16 v[126:129], v[166:169], v[204:207], v[126:129]
	v_mfma_f32_16x16x32_bf16 v[122:125], v[174:177], v[204:207], v[122:125]
	v_mfma_f32_16x16x32_bf16 v[110:113], v[166:169], v[212:215], v[110:113]
	v_mfma_f32_16x16x32_bf16 v[106:109], v[174:177], v[212:215], v[106:109]
	v_mfma_f32_16x16x32_bf16 v[94:97], v[166:169], v[220:223], v[94:97]
	v_mfma_f32_16x16x32_bf16 v[90:93], v[174:177], v[220:223], v[90:93]
	v_mfma_f32_16x16x32_bf16 v[78:81], v[166:169], v[228:231], v[78:81]
	v_mfma_f32_16x16x32_bf16 v[74:77], v[174:177], v[228:231], v[74:77]
	v_mfma_f32_16x16x32_bf16 v[118:121], v[178:181], v[200:203], v[118:121]
	v_mfma_f32_16x16x32_bf16 v[114:117], v[186:189], v[200:203], v[114:117]
	v_mfma_f32_16x16x32_bf16 v[102:105], v[178:181], v[208:211], v[102:105]
	v_mfma_f32_16x16x32_bf16 v[98:101], v[186:189], v[208:211], v[98:101]
	v_mfma_f32_16x16x32_bf16 v[86:89], v[178:181], v[216:219], v[86:89]
	v_mfma_f32_16x16x32_bf16 v[82:85], v[186:189], v[216:219], v[82:85]
	v_mfma_f32_16x16x32_bf16 v[70:73], v[178:181], v[224:227], v[70:73]
	v_mfma_f32_16x16x32_bf16 v[66:69], v[186:189], v[224:227], v[66:69]
	v_mfma_f32_16x16x32_bf16 v[118:121], v[182:185], v[204:207], v[118:121]
	v_mfma_f32_16x16x32_bf16 v[114:117], v[190:193], v[204:207], v[114:117]
	v_mfma_f32_16x16x32_bf16 v[102:105], v[182:185], v[212:215], v[102:105]
	v_mfma_f32_16x16x32_bf16 v[98:101], v[190:193], v[212:215], v[98:101]
	v_mfma_f32_16x16x32_bf16 v[86:89], v[182:185], v[220:223], v[86:89]
	v_mfma_f32_16x16x32_bf16 v[82:85], v[190:193], v[220:223], v[82:85]
	v_mfma_f32_16x16x32_bf16 v[70:73], v[182:185], v[228:231], v[70:73]
	v_mfma_f32_16x16x32_bf16 v[66:69], v[190:193], v[228:231], v[66:69]
	s_barrier
	s_add_i32 s70, s70, s52
	s_mov_b32 m0, s70
	ds_read_b128 v[200:203], v151 offset:16384
	ds_read_b128 v[204:207], v151 offset:17408
	ds_read_b128 v[208:211], v151 offset:18432
	ds_read_b128 v[212:215], v151 offset:19456
	ds_read_b128 v[216:219], v151 offset:20480
	ds_read_b128 v[220:223], v151 offset:21504
	ds_read_b128 v[224:227], v151 offset:22528
	ds_read_b128 v[228:231], v151 offset:23552
	global_load_lds_dwordx4 v158, s[36:37]
	s_add_i32 m0, s70, 0x2000
	s_add_u32 s70, s36, 0x80000
	s_addc_u32 s71, s37, 0
	s_add_i32 s75, s75, s52
	global_load_lds_dwordx4 v134, s[36:37]
	s_mov_b32 m0, s75
	s_nop 0
	global_load_lds_dwordx4 v158, s[70:71]
	s_add_i32 m0, s75, 0x2000
	s_nop 0
	global_load_lds_dwordx4 v134, s[70:71]
	s_waitcnt vmcnt(6)
	s_waitcnt lgkmcnt(0)
	s_barrier
	v_mfma_f32_16x16x32_bf16 v[62:65], v[152:155], v[200:203], v[62:65]
	v_mfma_f32_16x16x32_bf16 v[58:61], v[170:173], v[200:203], v[58:61]
	v_mfma_f32_16x16x32_bf16 v[46:49], v[152:155], v[208:211], v[46:49]
	v_mfma_f32_16x16x32_bf16 v[42:45], v[170:173], v[208:211], v[42:45]
	v_mfma_f32_16x16x32_bf16 v[30:33], v[152:155], v[216:219], v[30:33]
	v_mfma_f32_16x16x32_bf16 v[26:29], v[170:173], v[216:219], v[26:29]
	v_mfma_f32_16x16x32_bf16 v[14:17], v[152:155], v[224:227], v[14:17]
	v_mfma_f32_16x16x32_bf16 v[10:13], v[170:173], v[224:227], v[10:13]
	v_mfma_f32_16x16x32_bf16 v[62:65], v[166:169], v[204:207], v[62:65]
	v_mfma_f32_16x16x32_bf16 v[58:61], v[174:177], v[204:207], v[58:61]
	v_mfma_f32_16x16x32_bf16 v[46:49], v[166:169], v[212:215], v[46:49]
	v_mfma_f32_16x16x32_bf16 v[42:45], v[174:177], v[212:215], v[42:45]
	v_mfma_f32_16x16x32_bf16 v[30:33], v[166:169], v[220:223], v[30:33]
	v_mfma_f32_16x16x32_bf16 v[26:29], v[174:177], v[220:223], v[26:29]
	v_mfma_f32_16x16x32_bf16 v[14:17], v[166:169], v[228:231], v[14:17]
	v_mfma_f32_16x16x32_bf16 v[10:13], v[174:177], v[228:231], v[10:13]
	v_mfma_f32_16x16x32_bf16 v[54:57], v[178:181], v[200:203], v[54:57]
	v_mfma_f32_16x16x32_bf16 v[50:53], v[186:189], v[200:203], v[50:53]
	v_mfma_f32_16x16x32_bf16 v[38:41], v[178:181], v[208:211], v[38:41]
	v_mfma_f32_16x16x32_bf16 v[34:37], v[186:189], v[208:211], v[34:37]
	v_mfma_f32_16x16x32_bf16 v[22:25], v[178:181], v[216:219], v[22:25]
	v_mfma_f32_16x16x32_bf16 v[18:21], v[186:189], v[216:219], v[18:21]
	v_mfma_f32_16x16x32_bf16 v[6:9], v[178:181], v[224:227], v[6:9]
	v_mfma_f32_16x16x32_bf16 v[2:5], v[186:189], v[224:227], v[2:5]
	v_mfma_f32_16x16x32_bf16 v[54:57], v[182:185], v[204:207], v[54:57]
	v_mfma_f32_16x16x32_bf16 v[50:53], v[190:193], v[204:207], v[50:53]
	v_mfma_f32_16x16x32_bf16 v[38:41], v[182:185], v[212:215], v[38:41]
	v_mfma_f32_16x16x32_bf16 v[34:37], v[190:193], v[212:215], v[34:37]
	v_mfma_f32_16x16x32_bf16 v[22:25], v[182:185], v[220:223], v[22:25]
	v_mfma_f32_16x16x32_bf16 v[18:21], v[190:193], v[220:223], v[18:21]
	v_mfma_f32_16x16x32_bf16 v[6:9], v[182:185], v[228:231], v[6:9]
	v_mfma_f32_16x16x32_bf16 v[2:5], v[190:193], v[228:231], v[2:5]
	s_barrier
; #define PG8_STAGE(bufoff, gbase, voff) do { _Pragma("unroll") for (int _i = 0; _i < 2; ++_i) \
;         __builtin_amdgcn_global_load_lds((const unsigned*)((const char*)(gbase) + (voff)[_i]), (PG8_LAS unsigned*)(lds + (bufoff) + ldsw + _i * 8192), 16, 0, 0); } while (0)
; #define PG8_LDA(dst, b, h) do { _Pragma("unroll") for (int m = 0; m < 4; ++m) _Pragma("unroll") for (int k = 0; k < 2; ++k) dst[m][k] = *(const PG8_LAS bf16x8*)(lds + PG8_SA(b, h) + aoff + m * 2048 + k * 1024); } while (0)
; #define PG8_LDB(dst, b, h) do { _Pragma("unroll") for (int n = 0; n < 2; ++n) _Pragma("unroll") for (int k = 0; k < 2; ++k) dst[n][k] = *(const PG8_LAS bf16x8*)(lds + PG8_SB(b, h) + boff + n * 2048 + k * 1024); } while (0)
; #define PG8_MMA(ai, bj, At, Bt) do { __builtin_amdgcn_s_setprio(1); _Pragma("unroll") for (int m = 0; m < 4; ++m) _Pragma("unroll") for (int n = 0; n < 2; ++n) _Pragma("unroll") for (int k = 0; k < 2; ++k) \
;         acc[ai][bj][m][n] = __builtin_amdgcn_mfma_f32_16x16x32_bf16(Bt[n][k], At[m][k], acc[ai][bj][m][n], 0, 0, 0); __builtin_amdgcn_s_setprio(0); } while (0)
; #define PG8_WAIT_V(n) asm volatile("s_waitcnt vmcnt(" #n ")" ::: "memory")
; #define PG8_WAIT_L(n) asm volatile("s_waitcnt lgkmcnt(" #n ")" ::: "memory")
; #define PG8_BAR __builtin_amdgcn_s_barrier()
; #define PG8_SCHED __builtin_amdgcn_sched_barrier(0)
; template <class Epi, class Sched, bool ALIGN_EPI = false, bool SP2 = false>
; __device__ __forceinline__ void gemm_phase(PG8_LAS unsigned char* lds, const Gemm g, const Sched& S, const Epi& E) {
;     ...
;             PG8_LDB(B0, 1, 0); PG8_LDB(B1, 1, 1); PG8_SCHED; PG8_LDA(At, 1, 0); PG8_STAGE(PG8_SA(0, 1), a2 + hstep, voffA);
;             PG8_WAIT_V(8); PG8_WAIT_L(0); PG8_BAR; PG8_MMA(0, 0, At, B0); PG8_MMA(0, 1, At, B1); PG8_BAR; PG8_SCHED;
;             PG8_LDA(At, 1, 1); PG8_STAGE(PG8_SB(1, 0), b3, voffB); PG8_STAGE(PG8_SB(1, 1), b3 + hstep, voffB); PG8_STAGE(PG8_SA(1, 0), a3, voffA);
;             PG8_WAIT_V(8); PG8_WAIT_L(0); PG8_BAR; PG8_MMA(1, 0, At, B0); PG8_MMA(1, 1, At, B1); PG8_BAR; PG8_SCHED;
;     ...
;         if constexpr (ALIGN_EPI) { if (wr == 0) PG8_BAR; }
	s_add_i32 s70, 0, 0x18000
	v_add_u32_e32 v142, s70, v148
	s_add_i32 s71, 0, 0x1c000
	ds_read_b128 v[152:155], v142
	ds_read_b128 v[166:169], v142 offset:1024
	ds_read_b128 v[170:173], v142 offset:2048
	ds_read_b128 v[174:177], v142 offset:3072
	v_add_u32_e32 v142, s71, v148
	ds_read_b128 v[178:181], v142
	ds_read_b128 v[182:185], v142 offset:1024
	ds_read_b128 v[186:189], v142 offset:2048
	ds_read_b128 v[190:193], v142 offset:3072
	s_mov_b32 m0, s53
	s_nop 0
	global_load_lds_dwordx4 v130, s[38:39]
	s_mov_b32 m0, s54
	s_nop 0
	global_load_lds_dwordx4 v132, s[38:39]
	s_add_u32 s38, s38, 0x80000
	s_addc_u32 s39, s39, 0
	s_mov_b32 m0, s55
	ds_read_b128 v[200:203], v151 offset:32768
	ds_read_b128 v[204:207], v151 offset:33792
	ds_read_b128 v[208:211], v151 offset:34816
	ds_read_b128 v[212:215], v151 offset:35840
	ds_read_b128 v[216:219], v151 offset:36864
	ds_read_b128 v[220:223], v151 offset:37888
	ds_read_b128 v[224:227], v151 offset:38912
	ds_read_b128 v[228:231], v151 offset:39936
	global_load_lds_dwordx4 v130, s[38:39]
	s_mov_b32 m0, s56
	s_nop 0
	global_load_lds_dwordx4 v132, s[38:39]
	s_waitcnt vmcnt(8)
	s_waitcnt lgkmcnt(0)
	s_barrier
	v_mfma_f32_16x16x32_bf16 v[126:129], v[152:155], v[200:203], v[126:129]
	v_mfma_f32_16x16x32_bf16 v[122:125], v[170:173], v[200:203], v[122:125]
	v_mfma_f32_16x16x32_bf16 v[110:113], v[152:155], v[208:211], v[110:113]
	v_mfma_f32_16x16x32_bf16 v[106:109], v[170:173], v[208:211], v[106:109]
	v_mfma_f32_16x16x32_bf16 v[94:97], v[152:155], v[216:219], v[94:97]
	v_mfma_f32_16x16x32_bf16 v[90:93], v[170:173], v[216:219], v[90:93]
	v_mfma_f32_16x16x32_bf16 v[78:81], v[152:155], v[224:227], v[78:81]
	v_mfma_f32_16x16x32_bf16 v[74:77], v[170:173], v[224:227], v[74:77]
	v_mfma_f32_16x16x32_bf16 v[126:129], v[166:169], v[204:207], v[126:129]
	v_mfma_f32_16x16x32_bf16 v[122:125], v[174:177], v[204:207], v[122:125]
	v_mfma_f32_16x16x32_bf16 v[110:113], v[166:169], v[212:215], v[110:113]
	v_mfma_f32_16x16x32_bf16 v[106:109], v[174:177], v[212:215], v[106:109]
	v_mfma_f32_16x16x32_bf16 v[94:97], v[166:169], v[220:223], v[94:97]
	v_mfma_f32_16x16x32_bf16 v[90:93], v[174:177], v[220:223], v[90:93]
	v_mfma_f32_16x16x32_bf16 v[78:81], v[166:169], v[228:231], v[78:81]
	v_mfma_f32_16x16x32_bf16 v[74:77], v[174:177], v[228:231], v[74:77]
	v_mfma_f32_16x16x32_bf16 v[118:121], v[178:181], v[200:203], v[118:121]
	v_mfma_f32_16x16x32_bf16 v[114:117], v[186:189], v[200:203], v[114:117]
	v_mfma_f32_16x16x32_bf16 v[102:105], v[178:181], v[208:211], v[102:105]
	v_mfma_f32_16x16x32_bf16 v[98:101], v[186:189], v[208:211], v[98:101]
	v_mfma_f32_16x16x32_bf16 v[86:89], v[178:181], v[216:219], v[86:89]
	v_mfma_f32_16x16x32_bf16 v[82:85], v[186:189], v[216:219], v[82:85]
	v_mfma_f32_16x16x32_bf16 v[70:73], v[178:181], v[224:227], v[70:73]
	v_mfma_f32_16x16x32_bf16 v[66:69], v[186:189], v[224:227], v[66:69]
	v_mfma_f32_16x16x32_bf16 v[118:121], v[182:185], v[204:207], v[118:121]
	v_mfma_f32_16x16x32_bf16 v[114:117], v[190:193], v[204:207], v[114:117]
	v_mfma_f32_16x16x32_bf16 v[102:105], v[182:185], v[212:215], v[102:105]
	v_mfma_f32_16x16x32_bf16 v[98:101], v[190:193], v[212:215], v[98:101]
	v_mfma_f32_16x16x32_bf16 v[86:89], v[182:185], v[220:223], v[86:89]
	v_mfma_f32_16x16x32_bf16 v[82:85], v[190:193], v[220:223], v[82:85]
	v_mfma_f32_16x16x32_bf16 v[70:73], v[182:185], v[228:231], v[70:73]
	v_mfma_f32_16x16x32_bf16 v[66:69], v[190:193], v[228:231], v[66:69]
	s_barrier
	s_add_i32 s38, s70, s52
	s_add_i32 m0, s38, 0xffffff80
	ds_read_b128 v[200:203], v151 offset:49152
	ds_read_b128 v[204:207], v151 offset:50176
	ds_read_b128 v[208:211], v151 offset:51200
	ds_read_b128 v[212:215], v151 offset:52224
	ds_read_b128 v[216:219], v151 offset:53248
	ds_read_b128 v[220:223], v151 offset:54272
	ds_read_b128 v[224:227], v151 offset:55296
	ds_read_b128 v[228:231], v151 offset:56320
	global_load_lds_dwordx4 v158, s[36:37] offset:128
	s_add_i32 m0, s38, 0x1f80
	s_add_i32 s38, s71, s52
	global_load_lds_dwordx4 v134, s[36:37] offset:128
	s_add_u32 s36, s36, 0x80080
	s_addc_u32 s37, s37, 0
	s_mov_b32 m0, s38
	s_nop 0
	global_load_lds_dwordx4 v158, s[36:37]
	s_add_i32 m0, s38, 0x2000
	s_nop 0
	global_load_lds_dwordx4 v134, s[36:37]
	s_waitcnt vmcnt(6)
	s_waitcnt lgkmcnt(0)
	s_barrier
	v_mfma_f32_16x16x32_bf16 v[62:65], v[152:155], v[200:203], v[62:65]
	v_mfma_f32_16x16x32_bf16 v[58:61], v[170:173], v[200:203], v[58:61]
	v_mfma_f32_16x16x32_bf16 v[46:49], v[152:155], v[208:211], v[46:49]
	v_mfma_f32_16x16x32_bf16 v[42:45], v[170:173], v[208:211], v[42:45]
	v_mfma_f32_16x16x32_bf16 v[30:33], v[152:155], v[216:219], v[30:33]
	v_mfma_f32_16x16x32_bf16 v[26:29], v[170:173], v[216:219], v[26:29]
	v_mfma_f32_16x16x32_bf16 v[14:17], v[152:155], v[224:227], v[14:17]
	v_mfma_f32_16x16x32_bf16 v[10:13], v[170:173], v[224:227], v[10:13]
	v_mfma_f32_16x16x32_bf16 v[62:65], v[166:169], v[204:207], v[62:65]
	v_mfma_f32_16x16x32_bf16 v[58:61], v[174:177], v[204:207], v[58:61]
	v_mfma_f32_16x16x32_bf16 v[46:49], v[166:169], v[212:215], v[46:49]
	v_mfma_f32_16x16x32_bf16 v[42:45], v[174:177], v[212:215], v[42:45]
	v_mfma_f32_16x16x32_bf16 v[30:33], v[166:169], v[220:223], v[30:33]
	v_mfma_f32_16x16x32_bf16 v[26:29], v[174:177], v[220:223], v[26:29]
	v_mfma_f32_16x16x32_bf16 v[14:17], v[166:169], v[228:231], v[14:17]
	v_mfma_f32_16x16x32_bf16 v[10:13], v[174:177], v[228:231], v[10:13]
	v_mfma_f32_16x16x32_bf16 v[54:57], v[178:181], v[200:203], v[54:57]
	v_mfma_f32_16x16x32_bf16 v[50:53], v[186:189], v[200:203], v[50:53]
	v_mfma_f32_16x16x32_bf16 v[38:41], v[178:181], v[208:211], v[38:41]
	v_mfma_f32_16x16x32_bf16 v[34:37], v[186:189], v[208:211], v[34:37]
	v_mfma_f32_16x16x32_bf16 v[22:25], v[178:181], v[216:219], v[22:25]
	v_mfma_f32_16x16x32_bf16 v[18:21], v[186:189], v[216:219], v[18:21]
	v_mfma_f32_16x16x32_bf16 v[6:9], v[178:181], v[224:227], v[6:9]
	v_mfma_f32_16x16x32_bf16 v[2:5], v[186:189], v[224:227], v[2:5]
	v_mfma_f32_16x16x32_bf16 v[54:57], v[182:185], v[204:207], v[54:57]
	v_mfma_f32_16x16x32_bf16 v[50:53], v[190:193], v[204:207], v[50:53]
	v_mfma_f32_16x16x32_bf16 v[38:41], v[182:185], v[212:215], v[38:41]
	v_mfma_f32_16x16x32_bf16 v[34:37], v[190:193], v[212:215], v[34:37]
	v_mfma_f32_16x16x32_bf16 v[22:25], v[182:185], v[220:223], v[22:25]
	v_mfma_f32_16x16x32_bf16 v[18:21], v[190:193], v[220:223], v[18:21]
	v_mfma_f32_16x16x32_bf16 v[6:9], v[182:185], v[228:231], v[6:9]
	v_mfma_f32_16x16x32_bf16 v[2:5], v[190:193], v[228:231], v[2:5]
	s_barrier
	s_add_i32 s69, s69, 2
	s_add_u32 s30, s30, 0x100
	s_addc_u32 s31, s31, 0
	s_add_u32 s67, s67, 0x100
	s_addc_u32 s68, s68, 0
	s_cmp_gt_u32 s69, 29
	s_cbranch_scc0 .LBB0_139
	s_and_b64 vcc, exec, s[16:17]
	s_cbranch_vccz .LBB0_142
	s_barrier

; #define PG8_STAGE(bufoff, gbase, voff) do { _Pragma("unroll") for (int _i = 0; _i < 2; ++_i) \
;         __builtin_amdgcn_global_load_lds((const unsigned*)((const char*)(gbase) + (voff)[_i]), (PG8_LAS unsigned*)(lds + (bufoff) + ldsw + _i * 8192), 16, 0, 0); } while (0)
; #define PG8_LDA(dst, b, h) do { _Pragma("unroll") for (int m = 0; m < 4; ++m) _Pragma("unroll") for (int k = 0; k < 2; ++k) dst[m][k] = *(const PG8_LAS bf16x8*)(lds + PG8_SA(b, h) + aoff + m * 2048 + k * 1024); } while (0)
; #define PG8_LDB(dst, b, h) do { _Pragma("unroll") for (int n = 0; n < 2; ++n) _Pragma("unroll") for (int k = 0; k < 2; ++k) dst[n][k] = *(const PG8_LAS bf16x8*)(lds + PG8_SB(b, h) + boff + n * 2048 + k * 1024); } while (0)
; #define PG8_MMA(ai, bj, At, Bt) do { __builtin_amdgcn_s_setprio(1); _Pragma("unroll") for (int m = 0; m < 4; ++m) _Pragma("unroll") for (int n = 0; n < 2; ++n) _Pragma("unroll") for (int k = 0; k < 2; ++k) \
;         acc[ai][bj][m][n] = __builtin_amdgcn_mfma_f32_16x16x32_bf16(Bt[n][k], At[m][k], acc[ai][bj][m][n], 0, 0, 0); __builtin_amdgcn_s_setprio(0); } while (0)
; #define PG8_WAIT_V(n) asm volatile("s_waitcnt vmcnt(" #n ")" ::: "memory")
; #define PG8_BAR __builtin_amdgcn_s_barrier()
; template <class Epi, class Sched, bool ALIGN_EPI = false, bool SP2 = false>
; __device__ __forceinline__ void gemm_phase(PG8_LAS unsigned char* lds, const Gemm g, const Sched& S, const Epi& E) {
;     ...
;         for (int t = 0; t < nt; t += 2) {
;             const bool last = (t == nt - 2);
;             const char* a1 = cA + (size_t)(t + 1) * kstep;
;             const char* a2 = last ? nA : cA + (size_t)(t + 2) * kstep; const char* b2 = last ? nB : cB + (size_t)(t + 2) * kstep;
;             const char* a3 = a2 + kstep; const char* b3 = b2 + kstep;
;             if (last && has_next) S.a_ready(nxt);
;             if constexpr (SP2) {
;             PG8_LDB(B0, 0, 0); PG8_LDB(B1, 0, 1); PG8_SCHED; PG8_LDA(At, 0, 0); PG8_STAGE(PG8_SA(1, 1), a1 + hstep, voffA);
;             PG8_WAIT_V(8); PG8_WAIT_L(0); PG8_BAR; PG8_MMA(0, 0, At, B0); PG8_MMA(0, 1, At, B1); PG8_BAR; PG8_SCHED;
;             PG8_LDA(At, 0, 1); PG8_STAGE(PG8_SB(0, 0), b2, voffB); PG8_STAGE(PG8_SB(0, 1), b2 + hstep, voffB); PG8_STAGE(PG8_SA(0, 0), a2, voffA);
;             PG8_WAIT_V(8); PG8_WAIT_L(0); PG8_BAR; PG8_MMA(1, 0, At, B0); PG8_MMA(1, 1, At, B1); PG8_BAR; PG8_SCHED;
.LBB0_667:
	s_add_u32 s30, s0, 0xfff80080
	s_addc_u32 s31, s1, -1
	s_add_i32 s66, 0, 0x10000
	s_cmp_eq_u32 s63, 28
	s_cselect_b32 s37, s23, s31
	s_cselect_b32 s36, s59, s30
	s_cselect_b32 s31, s19, s62
	s_cselect_b32 s30, s60, s61
	s_add_i32 s68, 0, 0x14000
	v_add_u32_e32 v142, s66, v199
	v_add_u32_e32 v162, s68, v199
	ds_read_b128 v[130:133], v142
	ds_read_b128 v[134:137], v142 offset:1024
	ds_read_b128 v[138:141], v142 offset:2048
	ds_read_b128 v[142:145], v142 offset:3072
	ds_read_b128 v[146:149], v162
	ds_read_b128 v[150:153], v162 offset:1024
	ds_read_b128 v[154:157], v162 offset:2048
	ds_read_b128 v[162:165], v162 offset:3072
	s_add_u32 s98, s0, 0xfff80000
	s_addc_u32 s99, s1, -1
	s_mov_b32 m0, s54
	s_nop 0
	global_load_lds_dwordx4 v172, s[98:99]
	s_mov_b32 m0, s55
	s_nop 0
	global_load_lds_dwordx4 v174, s[98:99]
	s_add_i32 m0, s48, 0xc000
	ds_read_b128 v[176:179], v201
	ds_read_b128 v[180:183], v201 offset:1024
	ds_read_b128 v[184:187], v201 offset:2048
	ds_read_b128 v[188:191], v201 offset:3072
	ds_read_b128 v[202:205], v201 offset:4096
	ds_read_b128 v[206:209], v201 offset:5120
	ds_read_b128 v[210:213], v201 offset:6144
	ds_read_b128 v[214:217], v201 offset:7168
	global_load_lds_dwordx4 v172, s[0:1]
	s_add_i32 m0, s48, 0xe000
	s_nop 0
	global_load_lds_dwordx4 v174, s[0:1]
	s_waitcnt vmcnt(8)
	s_waitcnt lgkmcnt(0)
	s_barrier
	v_mfma_f32_16x16x32_bf16 v[126:129], v[130:133], v[176:179], v[126:129]
	v_mfma_f32_16x16x32_bf16 v[122:125], v[138:141], v[176:179], v[122:125]
	v_mfma_f32_16x16x32_bf16 v[110:113], v[130:133], v[184:187], v[110:113]
	v_mfma_f32_16x16x32_bf16 v[106:109], v[138:141], v[184:187], v[106:109]
	v_mfma_f32_16x16x32_bf16 v[94:97], v[130:133], v[202:205], v[94:97]
	v_mfma_f32_16x16x32_bf16 v[90:93], v[138:141], v[202:205], v[90:93]
	v_mfma_f32_16x16x32_bf16 v[78:81], v[130:133], v[210:213], v[78:81]
	v_mfma_f32_16x16x32_bf16 v[74:77], v[138:141], v[210:213], v[74:77]
	v_mfma_f32_16x16x32_bf16 v[126:129], v[134:137], v[180:183], v[126:129]
	v_mfma_f32_16x16x32_bf16 v[122:125], v[142:145], v[180:183], v[122:125]
	v_mfma_f32_16x16x32_bf16 v[110:113], v[134:137], v[188:191], v[110:113]
	v_mfma_f32_16x16x32_bf16 v[106:109], v[142:145], v[188:191], v[106:109]
	v_mfma_f32_16x16x32_bf16 v[94:97], v[134:137], v[206:209], v[94:97]
	v_mfma_f32_16x16x32_bf16 v[90:93], v[142:145], v[206:209], v[90:93]
	v_mfma_f32_16x16x32_bf16 v[78:81], v[134:137], v[214:217], v[78:81]
	v_mfma_f32_16x16x32_bf16 v[74:77], v[142:145], v[214:217], v[74:77]
	v_mfma_f32_16x16x32_bf16 v[118:121], v[146:149], v[176:179], v[118:121]
	v_mfma_f32_16x16x32_bf16 v[114:117], v[154:157], v[176:179], v[114:117]
	v_mfma_f32_16x16x32_bf16 v[102:105], v[146:149], v[184:187], v[102:105]
	v_mfma_f32_16x16x32_bf16 v[98:101], v[154:157], v[184:187], v[98:101]
	v_mfma_f32_16x16x32_bf16 v[86:89], v[146:149], v[202:205], v[86:89]
	v_mfma_f32_16x16x32_bf16 v[82:85], v[154:157], v[202:205], v[82:85]
	v_mfma_f32_16x16x32_bf16 v[70:73], v[146:149], v[210:213], v[70:73]
	v_mfma_f32_16x16x32_bf16 v[66:69], v[154:157], v[210:213], v[66:69]
	v_mfma_f32_16x16x32_bf16 v[118:121], v[150:153], v[180:183], v[118:121]
	v_mfma_f32_16x16x32_bf16 v[114:117], v[162:165], v[180:183], v[114:117]
	v_mfma_f32_16x16x32_bf16 v[102:105], v[150:153], v[188:191], v[102:105]
	v_mfma_f32_16x16x32_bf16 v[98:101], v[162:165], v[188:191], v[98:101]
	v_mfma_f32_16x16x32_bf16 v[86:89], v[150:153], v[206:209], v[86:89]
	v_mfma_f32_16x16x32_bf16 v[82:85], v[162:165], v[206:209], v[82:85]
	v_mfma_f32_16x16x32_bf16 v[70:73], v[150:153], v[214:217], v[70:73]
	v_mfma_f32_16x16x32_bf16 v[66:69], v[162:165], v[214:217], v[66:69]
	s_barrier
	s_add_i32 s66, s66, s47
	s_mov_b32 m0, s66
	ds_read_b128 v[176:179], v201 offset:16384
	ds_read_b128 v[180:183], v201 offset:17408
	ds_read_b128 v[184:187], v201 offset:18432
	ds_read_b128 v[188:191], v201 offset:19456
	ds_read_b128 v[202:205], v201 offset:20480
	ds_read_b128 v[206:209], v201 offset:21504
	ds_read_b128 v[210:213], v201 offset:22528
	ds_read_b128 v[214:217], v201 offset:23552
	global_load_lds_dwordx4 v158, s[30:31]
	s_add_i32 m0, s66, 0x2000
	s_add_u32 s66, s30, 0x80000
	s_addc_u32 s67, s31, 0
	s_add_i32 s68, s68, s47
	global_load_lds_dwordx4 v166, s[30:31]
	s_mov_b32 m0, s68
	s_nop 0
	global_load_lds_dwordx4 v158, s[66:67]
	s_add_i32 m0, s68, 0x2000
	s_nop 0
	global_load_lds_dwordx4 v166, s[66:67]
	s_waitcnt vmcnt(6)
	s_waitcnt lgkmcnt(0)
	s_barrier
	v_mfma_f32_16x16x32_bf16 v[62:65], v[130:133], v[176:179], v[62:65]
	v_mfma_f32_16x16x32_bf16 v[58:61], v[138:141], v[176:179], v[58:61]
	v_mfma_f32_16x16x32_bf16 v[46:49], v[130:133], v[184:187], v[46:49]
	v_mfma_f32_16x16x32_bf16 v[42:45], v[138:141], v[184:187], v[42:45]
	v_mfma_f32_16x16x32_bf16 v[30:33], v[130:133], v[202:205], v[30:33]
	v_mfma_f32_16x16x32_bf16 v[26:29], v[138:141], v[202:205], v[26:29]
	v_mfma_f32_16x16x32_bf16 v[14:17], v[130:133], v[210:213], v[14:17]
	v_mfma_f32_16x16x32_bf16 v[10:13], v[138:141], v[210:213], v[10:13]
	v_mfma_f32_16x16x32_bf16 v[62:65], v[134:137], v[180:183], v[62:65]
	v_mfma_f32_16x16x32_bf16 v[58:61], v[142:145], v[180:183], v[58:61]
	v_mfma_f32_16x16x32_bf16 v[46:49], v[134:137], v[188:191], v[46:49]
	v_mfma_f32_16x16x32_bf16 v[42:45], v[142:145], v[188:191], v[42:45]
	v_mfma_f32_16x16x32_bf16 v[30:33], v[134:137], v[206:209], v[30:33]
	v_mfma_f32_16x16x32_bf16 v[26:29], v[142:145], v[206:209], v[26:29]
	v_mfma_f32_16x16x32_bf16 v[14:17], v[134:137], v[214:217], v[14:17]
	v_mfma_f32_16x16x32_bf16 v[10:13], v[142:145], v[214:217], v[10:13]
	v_mfma_f32_16x16x32_bf16 v[54:57], v[146:149], v[176:179], v[54:57]
	v_mfma_f32_16x16x32_bf16 v[50:53], v[154:157], v[176:179], v[50:53]
	v_mfma_f32_16x16x32_bf16 v[38:41], v[146:149], v[184:187], v[38:41]
	v_mfma_f32_16x16x32_bf16 v[34:37], v[154:157], v[184:187], v[34:37]
	v_mfma_f32_16x16x32_bf16 v[22:25], v[146:149], v[202:205], v[22:25]
	v_mfma_f32_16x16x32_bf16 v[18:21], v[154:157], v[202:205], v[18:21]
	v_mfma_f32_16x16x32_bf16 v[6:9], v[146:149], v[210:213], v[6:9]
	v_mfma_f32_16x16x32_bf16 v[2:5], v[154:157], v[210:213], v[2:5]
	v_mfma_f32_16x16x32_bf16 v[54:57], v[150:153], v[180:183], v[54:57]
	v_mfma_f32_16x16x32_bf16 v[50:53], v[162:165], v[180:183], v[50:53]
	v_mfma_f32_16x16x32_bf16 v[38:41], v[150:153], v[188:191], v[38:41]
	v_mfma_f32_16x16x32_bf16 v[34:37], v[162:165], v[188:191], v[34:37]
	v_mfma_f32_16x16x32_bf16 v[22:25], v[150:153], v[206:209], v[22:25]
	v_mfma_f32_16x16x32_bf16 v[18:21], v[162:165], v[206:209], v[18:21]
	v_mfma_f32_16x16x32_bf16 v[6:9], v[150:153], v[214:217], v[6:9]
	v_mfma_f32_16x16x32_bf16 v[2:5], v[162:165], v[214:217], v[2:5]
	s_barrier
; #define PG8_STAGE(bufoff, gbase, voff) do { _Pragma("unroll") for (int _i = 0; _i < 2; ++_i) \
;         __builtin_amdgcn_global_load_lds((const unsigned*)((const char*)(gbase) + (voff)[_i]), (PG8_LAS unsigned*)(lds + (bufoff) + ldsw + _i * 8192), 16, 0, 0); } while (0)
; #define PG8_LDA(dst, b, h) do { _Pragma("unroll") for (int m = 0; m < 4; ++m) _Pragma("unroll") for (int k = 0; k < 2; ++k) dst[m][k] = *(const PG8_LAS bf16x8*)(lds + PG8_SA(b, h) + aoff + m * 2048 + k * 1024); } while (0)
; #define PG8_LDB(dst, b, h) do { _Pragma("unroll") for (int n = 0; n < 2; ++n) _Pragma("unroll") for (int k = 0; k < 2; ++k) dst[n][k] = *(const PG8_LAS bf16x8*)(lds + PG8_SB(b, h) + boff + n * 2048 + k * 1024); } while (0)
; #define PG8_MMA(ai, bj, At, Bt) do { __builtin_amdgcn_s_setprio(1); _Pragma("unroll") for (int m = 0; m < 4; ++m) _Pragma("unroll") for (int n = 0; n < 2; ++n) _Pragma("unroll") for (int k = 0; k < 2; ++k) \
;         acc[ai][bj][m][n] = __builtin_amdgcn_mfma_f32_16x16x32_bf16(Bt[n][k], At[m][k], acc[ai][bj][m][n], 0, 0, 0); __builtin_amdgcn_s_setprio(0); } while (0)
; #define PG8_WAIT_V(n) asm volatile("s_waitcnt vmcnt(" #n ")" ::: "memory")
; #define PG8_WAIT_L(n) asm volatile("s_waitcnt lgkmcnt(" #n ")" ::: "memory")
; #define PG8_BAR __builtin_amdgcn_s_barrier()
; #define PG8_SCHED __builtin_amdgcn_sched_barrier(0)
; template <class Epi, class Sched, bool ALIGN_EPI = false, bool SP2 = false>
; __device__ __forceinline__ void gemm_phase(PG8_LAS unsigned char* lds, const Gemm g, const Sched& S, const Epi& E) {
;     ...
;             PG8_LDB(B0, 1, 0); PG8_LDB(B1, 1, 1); PG8_SCHED; PG8_LDA(At, 1, 0); PG8_STAGE(PG8_SA(0, 1), a2 + hstep, voffA);
;             PG8_WAIT_V(8); PG8_WAIT_L(0); PG8_BAR; PG8_MMA(0, 0, At, B0); PG8_MMA(0, 1, At, B1); PG8_BAR; PG8_SCHED;
;             PG8_LDA(At, 1, 1); PG8_STAGE(PG8_SB(1, 0), b3, voffB); PG8_STAGE(PG8_SB(1, 1), b3 + hstep, voffB); PG8_STAGE(PG8_SA(1, 0), a3, voffA);
;             PG8_WAIT_V(8); PG8_WAIT_L(0); PG8_BAR; PG8_MMA(1, 0, At, B0); PG8_MMA(1, 1, At, B1); PG8_BAR; PG8_SCHED;
;     ...
;         if constexpr (ALIGN_EPI) { if (wr == 0) PG8_BAR; }
	s_add_i32 s66, 0, 0x18000
	s_add_i32 s67, 0, 0x1c000
	v_add_u32_e32 v142, s66, v199
	v_add_u32_e32 v162, s67, v199
	ds_read_b128 v[130:133], v142
	ds_read_b128 v[134:137], v142 offset:1024
	ds_read_b128 v[138:141], v142 offset:2048
	ds_read_b128 v[142:145], v142 offset:3072
	ds_read_b128 v[146:149], v162
	ds_read_b128 v[150:153], v162 offset:1024
	ds_read_b128 v[154:157], v162 offset:2048
	ds_read_b128 v[162:165], v162 offset:3072
	s_mov_b32 m0, s48
	s_nop 0
	global_load_lds_dwordx4 v170, s[36:37]
	s_mov_b32 m0, s49
	s_nop 0
	global_load_lds_dwordx4 v168, s[36:37]
	s_add_u32 s36, s36, 0x80000
	s_addc_u32 s37, s37, 0
	s_mov_b32 m0, s50
	ds_read_b128 v[176:179], v201 offset:32768
	ds_read_b128 v[180:183], v201 offset:33792
	ds_read_b128 v[184:187], v201 offset:34816
	ds_read_b128 v[188:191], v201 offset:35840
	ds_read_b128 v[202:205], v201 offset:36864
	ds_read_b128 v[206:209], v201 offset:37888
	ds_read_b128 v[210:213], v201 offset:38912
	ds_read_b128 v[214:217], v201 offset:39936
	global_load_lds_dwordx4 v170, s[36:37]
	s_mov_b32 m0, s51
	s_nop 0
	global_load_lds_dwordx4 v168, s[36:37]
	s_waitcnt vmcnt(8)
	s_waitcnt lgkmcnt(0)
	s_barrier
	v_mfma_f32_16x16x32_bf16 v[126:129], v[130:133], v[176:179], v[126:129]
	v_mfma_f32_16x16x32_bf16 v[122:125], v[138:141], v[176:179], v[122:125]
	v_mfma_f32_16x16x32_bf16 v[110:113], v[130:133], v[184:187], v[110:113]
	v_mfma_f32_16x16x32_bf16 v[106:109], v[138:141], v[184:187], v[106:109]
	v_mfma_f32_16x16x32_bf16 v[94:97], v[130:133], v[202:205], v[94:97]
	v_mfma_f32_16x16x32_bf16 v[90:93], v[138:141], v[202:205], v[90:93]
	v_mfma_f32_16x16x32_bf16 v[78:81], v[130:133], v[210:213], v[78:81]
	v_mfma_f32_16x16x32_bf16 v[74:77], v[138:141], v[210:213], v[74:77]
	v_mfma_f32_16x16x32_bf16 v[126:129], v[134:137], v[180:183], v[126:129]
	v_mfma_f32_16x16x32_bf16 v[122:125], v[142:145], v[180:183], v[122:125]
	v_mfma_f32_16x16x32_bf16 v[110:113], v[134:137], v[188:191], v[110:113]
	v_mfma_f32_16x16x32_bf16 v[106:109], v[142:145], v[188:191], v[106:109]
	v_mfma_f32_16x16x32_bf16 v[94:97], v[134:137], v[206:209], v[94:97]
	v_mfma_f32_16x16x32_bf16 v[90:93], v[142:145], v[206:209], v[90:93]
	v_mfma_f32_16x16x32_bf16 v[78:81], v[134:137], v[214:217], v[78:81]
	v_mfma_f32_16x16x32_bf16 v[74:77], v[142:145], v[214:217], v[74:77]
	v_mfma_f32_16x16x32_bf16 v[118:121], v[146:149], v[176:179], v[118:121]
	v_mfma_f32_16x16x32_bf16 v[114:117], v[154:157], v[176:179], v[114:117]
	v_mfma_f32_16x16x32_bf16 v[102:105], v[146:149], v[184:187], v[102:105]
	v_mfma_f32_16x16x32_bf16 v[98:101], v[154:157], v[184:187], v[98:101]
	v_mfma_f32_16x16x32_bf16 v[86:89], v[146:149], v[202:205], v[86:89]
	v_mfma_f32_16x16x32_bf16 v[82:85], v[154:157], v[202:205], v[82:85]
	v_mfma_f32_16x16x32_bf16 v[70:73], v[146:149], v[210:213], v[70:73]
	v_mfma_f32_16x16x32_bf16 v[66:69], v[154:157], v[210:213], v[66:69]
	v_mfma_f32_16x16x32_bf16 v[118:121], v[150:153], v[180:183], v[118:121]
	v_mfma_f32_16x16x32_bf16 v[114:117], v[162:165], v[180:183], v[114:117]
	v_mfma_f32_16x16x32_bf16 v[102:105], v[150:153], v[188:191], v[102:105]
	v_mfma_f32_16x16x32_bf16 v[98:101], v[162:165], v[188:191], v[98:101]
	v_mfma_f32_16x16x32_bf16 v[86:89], v[150:153], v[206:209], v[86:89]
	v_mfma_f32_16x16x32_bf16 v[82:85], v[162:165], v[206:209], v[82:85]
	v_mfma_f32_16x16x32_bf16 v[70:73], v[150:153], v[214:217], v[70:73]
	v_mfma_f32_16x16x32_bf16 v[66:69], v[162:165], v[214:217], v[66:69]
	s_barrier
	s_add_i32 s36, s66, s47
	s_add_i32 m0, s36, 0xffffff80
	ds_read_b128 v[176:179], v201 offset:49152
	ds_read_b128 v[180:183], v201 offset:50176
	ds_read_b128 v[184:187], v201 offset:51200
	ds_read_b128 v[188:191], v201 offset:52224
	ds_read_b128 v[202:205], v201 offset:53248
	ds_read_b128 v[206:209], v201 offset:54272
	ds_read_b128 v[210:213], v201 offset:55296
	ds_read_b128 v[214:217], v201 offset:56320
	global_load_lds_dwordx4 v158, s[30:31] offset:128
	s_add_i32 m0, s36, 0x1f80
	s_add_i32 s36, s67, s47
	global_load_lds_dwordx4 v166, s[30:31] offset:128
	s_add_u32 s30, s30, 0x80080
	s_addc_u32 s31, s31, 0
	s_mov_b32 m0, s36
	s_nop 0
	global_load_lds_dwordx4 v158, s[30:31]
	s_add_i32 m0, s36, 0x2000
	s_nop 0
	global_load_lds_dwordx4 v166, s[30:31]
	s_waitcnt vmcnt(6)
	s_waitcnt lgkmcnt(0)
	s_barrier
	v_mfma_f32_16x16x32_bf16 v[62:65], v[130:133], v[176:179], v[62:65]
	v_mfma_f32_16x16x32_bf16 v[58:61], v[138:141], v[176:179], v[58:61]
	v_mfma_f32_16x16x32_bf16 v[46:49], v[130:133], v[184:187], v[46:49]
	v_mfma_f32_16x16x32_bf16 v[42:45], v[138:141], v[184:187], v[42:45]
	v_mfma_f32_16x16x32_bf16 v[30:33], v[130:133], v[202:205], v[30:33]
	v_mfma_f32_16x16x32_bf16 v[26:29], v[138:141], v[202:205], v[26:29]
	v_mfma_f32_16x16x32_bf16 v[14:17], v[130:133], v[210:213], v[14:17]
	v_mfma_f32_16x16x32_bf16 v[10:13], v[138:141], v[210:213], v[10:13]
	v_mfma_f32_16x16x32_bf16 v[62:65], v[134:137], v[180:183], v[62:65]
	v_mfma_f32_16x16x32_bf16 v[58:61], v[142:145], v[180:183], v[58:61]
	v_mfma_f32_16x16x32_bf16 v[46:49], v[134:137], v[188:191], v[46:49]
	v_mfma_f32_16x16x32_bf16 v[42:45], v[142:145], v[188:191], v[42:45]
	v_mfma_f32_16x16x32_bf16 v[30:33], v[134:137], v[206:209], v[30:33]
	v_mfma_f32_16x16x32_bf16 v[26:29], v[142:145], v[206:209], v[26:29]
	v_mfma_f32_16x16x32_bf16 v[14:17], v[134:137], v[214:217], v[14:17]
	v_mfma_f32_16x16x32_bf16 v[10:13], v[142:145], v[214:217], v[10:13]
	v_mfma_f32_16x16x32_bf16 v[54:57], v[146:149], v[176:179], v[54:57]
	v_mfma_f32_16x16x32_bf16 v[50:53], v[154:157], v[176:179], v[50:53]
	v_mfma_f32_16x16x32_bf16 v[38:41], v[146:149], v[184:187], v[38:41]
	v_mfma_f32_16x16x32_bf16 v[34:37], v[154:157], v[184:187], v[34:37]
	v_mfma_f32_16x16x32_bf16 v[22:25], v[146:149], v[202:205], v[22:25]
	v_mfma_f32_16x16x32_bf16 v[18:21], v[154:157], v[202:205], v[18:21]
	v_mfma_f32_16x16x32_bf16 v[6:9], v[146:149], v[210:213], v[6:9]
	v_mfma_f32_16x16x32_bf16 v[2:5], v[154:157], v[210:213], v[2:5]
	v_mfma_f32_16x16x32_bf16 v[54:57], v[150:153], v[180:183], v[54:57]
	v_mfma_f32_16x16x32_bf16 v[50:53], v[162:165], v[180:183], v[50:53]
	v_mfma_f32_16x16x32_bf16 v[38:41], v[150:153], v[188:191], v[38:41]
	v_mfma_f32_16x16x32_bf16 v[34:37], v[162:165], v[188:191], v[34:37]
	v_mfma_f32_16x16x32_bf16 v[22:25], v[150:153], v[206:209], v[22:25]
	v_mfma_f32_16x16x32_bf16 v[18:21], v[162:165], v[206:209], v[18:21]
	v_mfma_f32_16x16x32_bf16 v[6:9], v[150:153], v[214:217], v[6:9]
	v_mfma_f32_16x16x32_bf16 v[2:5], v[162:165], v[214:217], v[2:5]
	s_barrier
	s_add_i32 s63, s63, 2
	s_add_u32 s0, s0, 0x100
	s_addc_u32 s1, s1, 0
	s_add_u32 s61, s61, 0x100
	s_addc_u32 s62, s62, 0
	s_cmp_gt_u32 s63, 29
	s_cbranch_scc0 .LBB0_667
	s_and_b64 vcc, exec, s[16:17]
	s_cbranch_vccz .LBB0_670
	s_barrier

; #define PG8_STAGE(bufoff, gbase, voff) do { _Pragma("unroll") for (int _i = 0; _i < 2; ++_i) \
;         __builtin_amdgcn_global_load_lds((const unsigned*)((const char*)(gbase) + (voff)[_i]), (PG8_LAS unsigned*)(lds + (bufoff) + ldsw + _i * 8192), 16, 0, 0); } while (0)
; #define PG8_LDA(dst, b, h) do { _Pragma("unroll") for (int m = 0; m < 4; ++m) _Pragma("unroll") for (int k = 0; k < 2; ++k) dst[m][k] = *(const PG8_LAS bf16x8*)(lds + PG8_SA(b, h) + aoff + m * 2048 + k * 1024); } while (0)
; #define PG8_LDB(dst, b, h) do { _Pragma("unroll") for (int n = 0; n < 2; ++n) _Pragma("unroll") for (int k = 0; k < 2; ++k) dst[n][k] = *(const PG8_LAS bf16x8*)(lds + PG8_SB(b, h) + boff + n * 2048 + k * 1024); } while (0)
; #define PG8_MMA(ai, bj, At, Bt) do { __builtin_amdgcn_s_setprio(1); _Pragma("unroll") for (int m = 0; m < 4; ++m) _Pragma("unroll") for (int n = 0; n < 2; ++n) _Pragma("unroll") for (int k = 0; k < 2; ++k) \
;         acc[ai][bj][m][n] = __builtin_amdgcn_mfma_f32_16x16x32_bf16(Bt[n][k], At[m][k], acc[ai][bj][m][n], 0, 0, 0); __builtin_amdgcn_s_setprio(0); } while (0)
; #define PG8_WAIT_V(n) asm volatile("s_waitcnt vmcnt(" #n ")" ::: "memory")
; #define PG8_WAIT_L(n) asm volatile("s_waitcnt lgkmcnt(" #n ")" ::: "memory")
; template <class Epi, class Sched, bool ALIGN_EPI = false, bool SP2 = false>
; __device__ __forceinline__ void gemm_phase(PG8_LAS unsigned char* lds, const Gemm g, const Sched& S, const Epi& E) {
;     ...
;             const bool last = (t == nt - 2);
;             const char* a1 = cA + (size_t)(t + 1) * kstep;
;             const char* a2 = last ? nA : cA + (size_t)(t + 2) * kstep; const char* b2 = last ? nB : cB + (size_t)(t + 2) * kstep;
;             const char* a3 = a2 + kstep; const char* b3 = b2 + kstep;
;             if (last && has_next) S.a_ready(nxt);
;             if constexpr (SP2) {
;             PG8_LDB(B0, 0, 0); PG8_LDB(B1, 0, 1); PG8_SCHED; PG8_LDA(At, 0, 0); PG8_STAGE(PG8_SA(1, 1), a1 + hstep, voffA);
;             PG8_WAIT_V(8); PG8_WAIT_L(0); PG8_BAR; PG8_MMA(0, 0, At, B0); PG8_MMA(0, 1, At, B1); PG8_BAR; PG8_SCHED;
;             PG8_LDA(At, 0, 1); PG8_STAGE(PG8_SB(0, 0), b2, voffB); PG8_STAGE(PG8_SB(0, 1), b2 + hstep, voffB); PG8_STAGE(PG8_SA(0, 0), a2, voffA);
;             PG8_WAIT_V(8); PG8_WAIT_L(0); PG8_BAR; PG8_MMA(1, 0, At, B0); PG8_MMA(1, 1, At, B1); PG8_BAR; PG8_SCHED;
.LBB0_762:
	s_add_u32 s30, s0, 0xfff80080
	s_addc_u32 s31, s1, -1
	s_add_i32 s67, 0, 0x10000
	s_cmp_eq_u32 s66, 28
	s_cselect_b32 s37, s23, s31
	s_cselect_b32 s36, s60, s30
	v_add_u32_e32 v151, s67, v146
	s_cselect_b32 s31, s19, s63
	s_cselect_b32 s30, s61, s62
	s_add_i32 s70, 0, 0x14000
	ds_read_b128 v[140:143], v151
	ds_read_b128 v[152:155], v151 offset:1024
	ds_read_b128 v[162:165], v151 offset:2048
	ds_read_b128 v[166:169], v151 offset:3072
	v_add_u32_e32 v151, s70, v146
	ds_read_b128 v[170:173], v151
	ds_read_b128 v[174:177], v151 offset:1024
	ds_read_b128 v[178:181], v151 offset:2048
	ds_read_b128 v[182:185], v151 offset:3072
	s_add_u32 s98, s0, 0xfff80000
	s_addc_u32 s99, s1, -1
	s_mov_b32 m0, s52
	s_nop 0
	global_load_lds_dwordx4 v136, s[98:99]
	s_mov_b32 m0, s53
	s_nop 0
	global_load_lds_dwordx4 v138, s[98:99]
	s_add_i32 m0, s47, 0xc000
	ds_read_b128 v[186:189], v150
	ds_read_b128 v[190:193], v150 offset:1024
	ds_read_b128 v[200:203], v150 offset:2048
	ds_read_b128 v[204:207], v150 offset:3072
	ds_read_b128 v[208:211], v150 offset:4096
	ds_read_b128 v[212:215], v150 offset:5120
	ds_read_b128 v[216:219], v150 offset:6144
	ds_read_b128 v[220:223], v150 offset:7168
	global_load_lds_dwordx4 v136, s[0:1]
	s_add_i32 m0, s47, 0xe000
	s_nop 0
	global_load_lds_dwordx4 v138, s[0:1]
	s_waitcnt vmcnt(8)
	s_waitcnt lgkmcnt(0)
	s_barrier
	v_mfma_f32_16x16x32_bf16 v[126:129], v[140:143], v[186:189], v[126:129]
	v_mfma_f32_16x16x32_bf16 v[122:125], v[162:165], v[186:189], v[122:125]
	v_mfma_f32_16x16x32_bf16 v[110:113], v[140:143], v[200:203], v[110:113]
	v_mfma_f32_16x16x32_bf16 v[106:109], v[162:165], v[200:203], v[106:109]
	v_mfma_f32_16x16x32_bf16 v[94:97], v[140:143], v[208:211], v[94:97]
	v_mfma_f32_16x16x32_bf16 v[90:93], v[162:165], v[208:211], v[90:93]
	v_mfma_f32_16x16x32_bf16 v[78:81], v[140:143], v[216:219], v[78:81]
	v_mfma_f32_16x16x32_bf16 v[74:77], v[162:165], v[216:219], v[74:77]
	v_mfma_f32_16x16x32_bf16 v[126:129], v[152:155], v[190:193], v[126:129]
	v_mfma_f32_16x16x32_bf16 v[122:125], v[166:169], v[190:193], v[122:125]
	v_mfma_f32_16x16x32_bf16 v[110:113], v[152:155], v[204:207], v[110:113]
	v_mfma_f32_16x16x32_bf16 v[106:109], v[166:169], v[204:207], v[106:109]
	v_mfma_f32_16x16x32_bf16 v[94:97], v[152:155], v[212:215], v[94:97]
	v_mfma_f32_16x16x32_bf16 v[90:93], v[166:169], v[212:215], v[90:93]
	v_mfma_f32_16x16x32_bf16 v[78:81], v[152:155], v[220:223], v[78:81]
	v_mfma_f32_16x16x32_bf16 v[74:77], v[166:169], v[220:223], v[74:77]
	v_mfma_f32_16x16x32_bf16 v[118:121], v[170:173], v[186:189], v[118:121]
	v_mfma_f32_16x16x32_bf16 v[114:117], v[178:181], v[186:189], v[114:117]
	v_mfma_f32_16x16x32_bf16 v[102:105], v[170:173], v[200:203], v[102:105]
	v_mfma_f32_16x16x32_bf16 v[98:101], v[178:181], v[200:203], v[98:101]
	v_mfma_f32_16x16x32_bf16 v[86:89], v[170:173], v[208:211], v[86:89]
	v_mfma_f32_16x16x32_bf16 v[82:85], v[178:181], v[208:211], v[82:85]
	v_mfma_f32_16x16x32_bf16 v[70:73], v[170:173], v[216:219], v[70:73]
	v_mfma_f32_16x16x32_bf16 v[66:69], v[178:181], v[216:219], v[66:69]
	v_mfma_f32_16x16x32_bf16 v[118:121], v[174:177], v[190:193], v[118:121]
	v_mfma_f32_16x16x32_bf16 v[114:117], v[182:185], v[190:193], v[114:117]
	v_mfma_f32_16x16x32_bf16 v[102:105], v[174:177], v[204:207], v[102:105]
	v_mfma_f32_16x16x32_bf16 v[98:101], v[182:185], v[204:207], v[98:101]
	v_mfma_f32_16x16x32_bf16 v[86:89], v[174:177], v[212:215], v[86:89]
	v_mfma_f32_16x16x32_bf16 v[82:85], v[182:185], v[212:215], v[82:85]
	v_mfma_f32_16x16x32_bf16 v[70:73], v[174:177], v[220:223], v[70:73]
	v_mfma_f32_16x16x32_bf16 v[66:69], v[182:185], v[220:223], v[66:69]
	s_barrier
	s_add_i32 s67, s67, s46
	s_mov_b32 m0, s67
	ds_read_b128 v[186:189], v150 offset:16384
	ds_read_b128 v[190:193], v150 offset:17408
	ds_read_b128 v[200:203], v150 offset:18432
	ds_read_b128 v[204:207], v150 offset:19456
	ds_read_b128 v[208:211], v150 offset:20480
	ds_read_b128 v[212:215], v150 offset:21504
	ds_read_b128 v[216:219], v150 offset:22528
	ds_read_b128 v[220:223], v150 offset:23552
	global_load_lds_dwordx4 v158, s[30:31]
	s_add_i32 m0, s67, 0x2000
	s_add_u32 s68, s30, 0x80000
	s_addc_u32 s69, s31, 0
	s_add_i32 s67, s70, s46
	global_load_lds_dwordx4 v134, s[30:31]
	s_mov_b32 m0, s67
	s_nop 0
	global_load_lds_dwordx4 v158, s[68:69]
	s_add_i32 m0, s67, 0x2000
	s_nop 0
	global_load_lds_dwordx4 v134, s[68:69]
	s_waitcnt vmcnt(6)
	s_waitcnt lgkmcnt(0)
	s_barrier
	v_mfma_f32_16x16x32_bf16 v[62:65], v[140:143], v[186:189], v[62:65]
	v_mfma_f32_16x16x32_bf16 v[58:61], v[162:165], v[186:189], v[58:61]
	v_mfma_f32_16x16x32_bf16 v[46:49], v[140:143], v[200:203], v[46:49]
	v_mfma_f32_16x16x32_bf16 v[42:45], v[162:165], v[200:203], v[42:45]
	v_mfma_f32_16x16x32_bf16 v[30:33], v[140:143], v[208:211], v[30:33]
	v_mfma_f32_16x16x32_bf16 v[26:29], v[162:165], v[208:211], v[26:29]
	v_mfma_f32_16x16x32_bf16 v[14:17], v[140:143], v[216:219], v[14:17]
	v_mfma_f32_16x16x32_bf16 v[10:13], v[162:165], v[216:219], v[10:13]
	v_mfma_f32_16x16x32_bf16 v[62:65], v[152:155], v[190:193], v[62:65]
	v_mfma_f32_16x16x32_bf16 v[58:61], v[166:169], v[190:193], v[58:61]
	v_mfma_f32_16x16x32_bf16 v[46:49], v[152:155], v[204:207], v[46:49]
	v_mfma_f32_16x16x32_bf16 v[42:45], v[166:169], v[204:207], v[42:45]
	v_mfma_f32_16x16x32_bf16 v[30:33], v[152:155], v[212:215], v[30:33]
	v_mfma_f32_16x16x32_bf16 v[26:29], v[166:169], v[212:215], v[26:29]
	v_mfma_f32_16x16x32_bf16 v[14:17], v[152:155], v[220:223], v[14:17]
	v_mfma_f32_16x16x32_bf16 v[10:13], v[166:169], v[220:223], v[10:13]
	v_mfma_f32_16x16x32_bf16 v[54:57], v[170:173], v[186:189], v[54:57]
	v_mfma_f32_16x16x32_bf16 v[50:53], v[178:181], v[186:189], v[50:53]
	v_mfma_f32_16x16x32_bf16 v[38:41], v[170:173], v[200:203], v[38:41]
	v_mfma_f32_16x16x32_bf16 v[34:37], v[178:181], v[200:203], v[34:37]
	v_mfma_f32_16x16x32_bf16 v[22:25], v[170:173], v[208:211], v[22:25]
	v_mfma_f32_16x16x32_bf16 v[18:21], v[178:181], v[208:211], v[18:21]
	v_mfma_f32_16x16x32_bf16 v[6:9], v[170:173], v[216:219], v[6:9]
	v_mfma_f32_16x16x32_bf16 v[2:5], v[178:181], v[216:219], v[2:5]
	v_mfma_f32_16x16x32_bf16 v[54:57], v[174:177], v[190:193], v[54:57]
	v_mfma_f32_16x16x32_bf16 v[50:53], v[182:185], v[190:193], v[50:53]
	v_mfma_f32_16x16x32_bf16 v[38:41], v[174:177], v[204:207], v[38:41]
	v_mfma_f32_16x16x32_bf16 v[34:37], v[182:185], v[204:207], v[34:37]
	v_mfma_f32_16x16x32_bf16 v[22:25], v[174:177], v[212:215], v[22:25]
	v_mfma_f32_16x16x32_bf16 v[18:21], v[182:185], v[212:215], v[18:21]
	v_mfma_f32_16x16x32_bf16 v[6:9], v[174:177], v[220:223], v[6:9]
	v_mfma_f32_16x16x32_bf16 v[2:5], v[182:185], v[220:223], v[2:5]
	s_barrier
; #define PG8_STAGE(bufoff, gbase, voff) do { _Pragma("unroll") for (int _i = 0; _i < 2; ++_i) \
;         __builtin_amdgcn_global_load_lds((const unsigned*)((const char*)(gbase) + (voff)[_i]), (PG8_LAS unsigned*)(lds + (bufoff) + ldsw + _i * 8192), 16, 0, 0); } while (0)
; #define PG8_LDA(dst, b, h) do { _Pragma("unroll") for (int m = 0; m < 4; ++m) _Pragma("unroll") for (int k = 0; k < 2; ++k) dst[m][k] = *(const PG8_LAS bf16x8*)(lds + PG8_SA(b, h) + aoff + m * 2048 + k * 1024); } while (0)
; #define PG8_LDB(dst, b, h) do { _Pragma("unroll") for (int n = 0; n < 2; ++n) _Pragma("unroll") for (int k = 0; k < 2; ++k) dst[n][k] = *(const PG8_LAS bf16x8*)(lds + PG8_SB(b, h) + boff + n * 2048 + k * 1024); } while (0)
; #define PG8_MMA(ai, bj, At, Bt) do { __builtin_amdgcn_s_setprio(1); _Pragma("unroll") for (int m = 0; m < 4; ++m) _Pragma("unroll") for (int n = 0; n < 2; ++n) _Pragma("unroll") for (int k = 0; k < 2; ++k) \
;         acc[ai][bj][m][n] = __builtin_amdgcn_mfma_f32_16x16x32_bf16(Bt[n][k], At[m][k], acc[ai][bj][m][n], 0, 0, 0); __builtin_amdgcn_s_setprio(0); } while (0)
; #define PG8_WAIT_V(n) asm volatile("s_waitcnt vmcnt(" #n ")" ::: "memory")
; #define PG8_WAIT_L(n) asm volatile("s_waitcnt lgkmcnt(" #n ")" ::: "memory")
; #define PG8_BAR __builtin_amdgcn_s_barrier()
; #define PG8_SCHED __builtin_amdgcn_sched_barrier(0)
; template <class Epi, class Sched, bool ALIGN_EPI = false, bool SP2 = false>
; __device__ __forceinline__ void gemm_phase(PG8_LAS unsigned char* lds, const Gemm g, const Sched& S, const Epi& E) {
;     ...
;         for (int t = 0; t < nt; t += 2) {
;     ...
;             PG8_LDB(B0, 1, 0); PG8_LDB(B1, 1, 1); PG8_SCHED; PG8_LDA(At, 1, 0); PG8_STAGE(PG8_SA(0, 1), a2 + hstep, voffA);
;             PG8_WAIT_V(8); PG8_WAIT_L(0); PG8_BAR; PG8_MMA(0, 0, At, B0); PG8_MMA(0, 1, At, B1); PG8_BAR; PG8_SCHED;
;             PG8_LDA(At, 1, 1); PG8_STAGE(PG8_SB(1, 0), b3, voffB); PG8_STAGE(PG8_SB(1, 1), b3 + hstep, voffB); PG8_STAGE(PG8_SA(1, 0), a3, voffA);
;             PG8_WAIT_V(8); PG8_WAIT_L(0); PG8_BAR; PG8_MMA(1, 0, At, B0); PG8_MMA(1, 1, At, B1); PG8_BAR; PG8_SCHED;
	s_add_i32 s67, 0, 0x18000
	v_add_u32_e32 v151, s67, v146
	s_add_i32 s68, 0, 0x1c000
	ds_read_b128 v[140:143], v151
	ds_read_b128 v[152:155], v151 offset:1024
	ds_read_b128 v[162:165], v151 offset:2048
	ds_read_b128 v[166:169], v151 offset:3072
	v_add_u32_e32 v151, s68, v146
	ds_read_b128 v[170:173], v151
	ds_read_b128 v[174:177], v151 offset:1024
	ds_read_b128 v[178:181], v151 offset:2048
	ds_read_b128 v[182:185], v151 offset:3072
	s_mov_b32 m0, s47
	s_nop 0
	global_load_lds_dwordx4 v130, s[36:37]
	s_mov_b32 m0, s48
	s_nop 0
	global_load_lds_dwordx4 v132, s[36:37]
	s_add_u32 s36, s36, 0x80000
	s_addc_u32 s37, s37, 0
	s_mov_b32 m0, s49
	ds_read_b128 v[186:189], v150 offset:32768
	ds_read_b128 v[190:193], v150 offset:33792
	ds_read_b128 v[200:203], v150 offset:34816
	ds_read_b128 v[204:207], v150 offset:35840
	ds_read_b128 v[208:211], v150 offset:36864
	ds_read_b128 v[212:215], v150 offset:37888
	ds_read_b128 v[216:219], v150 offset:38912
	ds_read_b128 v[220:223], v150 offset:39936
	global_load_lds_dwordx4 v130, s[36:37]
	s_mov_b32 m0, s50
	s_nop 0
	global_load_lds_dwordx4 v132, s[36:37]
	s_waitcnt vmcnt(8)
	s_waitcnt lgkmcnt(0)
	s_barrier
	v_mfma_f32_16x16x32_bf16 v[126:129], v[140:143], v[186:189], v[126:129]
	v_mfma_f32_16x16x32_bf16 v[122:125], v[162:165], v[186:189], v[122:125]
	v_mfma_f32_16x16x32_bf16 v[110:113], v[140:143], v[200:203], v[110:113]
	v_mfma_f32_16x16x32_bf16 v[106:109], v[162:165], v[200:203], v[106:109]
	v_mfma_f32_16x16x32_bf16 v[94:97], v[140:143], v[208:211], v[94:97]
	v_mfma_f32_16x16x32_bf16 v[90:93], v[162:165], v[208:211], v[90:93]
	v_mfma_f32_16x16x32_bf16 v[78:81], v[140:143], v[216:219], v[78:81]
	v_mfma_f32_16x16x32_bf16 v[74:77], v[162:165], v[216:219], v[74:77]
	v_mfma_f32_16x16x32_bf16 v[126:129], v[152:155], v[190:193], v[126:129]
	v_mfma_f32_16x16x32_bf16 v[122:125], v[166:169], v[190:193], v[122:125]
	v_mfma_f32_16x16x32_bf16 v[110:113], v[152:155], v[204:207], v[110:113]
	v_mfma_f32_16x16x32_bf16 v[106:109], v[166:169], v[204:207], v[106:109]
	v_mfma_f32_16x16x32_bf16 v[94:97], v[152:155], v[212:215], v[94:97]
	v_mfma_f32_16x16x32_bf16 v[90:93], v[166:169], v[212:215], v[90:93]
	v_mfma_f32_16x16x32_bf16 v[78:81], v[152:155], v[220:223], v[78:81]
	v_mfma_f32_16x16x32_bf16 v[74:77], v[166:169], v[220:223], v[74:77]
	v_mfma_f32_16x16x32_bf16 v[118:121], v[170:173], v[186:189], v[118:121]
	v_mfma_f32_16x16x32_bf16 v[114:117], v[178:181], v[186:189], v[114:117]
	v_mfma_f32_16x16x32_bf16 v[102:105], v[170:173], v[200:203], v[102:105]
	v_mfma_f32_16x16x32_bf16 v[98:101], v[178:181], v[200:203], v[98:101]
	v_mfma_f32_16x16x32_bf16 v[86:89], v[170:173], v[208:211], v[86:89]
	v_mfma_f32_16x16x32_bf16 v[82:85], v[178:181], v[208:211], v[82:85]
	v_mfma_f32_16x16x32_bf16 v[70:73], v[170:173], v[216:219], v[70:73]
	v_mfma_f32_16x16x32_bf16 v[66:69], v[178:181], v[216:219], v[66:69]
	v_mfma_f32_16x16x32_bf16 v[118:121], v[174:177], v[190:193], v[118:121]
	v_mfma_f32_16x16x32_bf16 v[114:117], v[182:185], v[190:193], v[114:117]
	v_mfma_f32_16x16x32_bf16 v[102:105], v[174:177], v[204:207], v[102:105]
	v_mfma_f32_16x16x32_bf16 v[98:101], v[182:185], v[204:207], v[98:101]
	v_mfma_f32_16x16x32_bf16 v[86:89], v[174:177], v[212:215], v[86:89]
	v_mfma_f32_16x16x32_bf16 v[82:85], v[182:185], v[212:215], v[82:85]
	v_mfma_f32_16x16x32_bf16 v[70:73], v[174:177], v[220:223], v[70:73]
	v_mfma_f32_16x16x32_bf16 v[66:69], v[182:185], v[220:223], v[66:69]
	s_barrier
	s_add_i32 s36, s67, s46
	s_add_i32 m0, s36, 0xffffff80
	ds_read_b128 v[186:189], v150 offset:49152
	ds_read_b128 v[190:193], v150 offset:50176
	ds_read_b128 v[200:203], v150 offset:51200
	ds_read_b128 v[204:207], v150 offset:52224
	ds_read_b128 v[208:211], v150 offset:53248
	ds_read_b128 v[212:215], v150 offset:54272
	ds_read_b128 v[216:219], v150 offset:55296
	ds_read_b128 v[220:223], v150 offset:56320
	global_load_lds_dwordx4 v158, s[30:31] offset:128
	s_add_i32 m0, s36, 0x1f80
	s_add_i32 s36, s68, s46
	global_load_lds_dwordx4 v134, s[30:31] offset:128
	s_add_u32 s30, s30, 0x80080
	s_addc_u32 s31, s31, 0
	s_mov_b32 m0, s36
	s_nop 0
	global_load_lds_dwordx4 v158, s[30:31]
	s_add_i32 m0, s36, 0x2000
	s_nop 0
	global_load_lds_dwordx4 v134, s[30:31]
	s_waitcnt vmcnt(6)
	s_waitcnt lgkmcnt(0)
	s_barrier
	v_mfma_f32_16x16x32_bf16 v[62:65], v[140:143], v[186:189], v[62:65]
	v_mfma_f32_16x16x32_bf16 v[58:61], v[162:165], v[186:189], v[58:61]
	v_mfma_f32_16x16x32_bf16 v[46:49], v[140:143], v[200:203], v[46:49]
	v_mfma_f32_16x16x32_bf16 v[42:45], v[162:165], v[200:203], v[42:45]
	v_mfma_f32_16x16x32_bf16 v[30:33], v[140:143], v[208:211], v[30:33]
	v_mfma_f32_16x16x32_bf16 v[26:29], v[162:165], v[208:211], v[26:29]
	v_mfma_f32_16x16x32_bf16 v[14:17], v[140:143], v[216:219], v[14:17]
	v_mfma_f32_16x16x32_bf16 v[10:13], v[162:165], v[216:219], v[10:13]
	v_mfma_f32_16x16x32_bf16 v[62:65], v[152:155], v[190:193], v[62:65]
	v_mfma_f32_16x16x32_bf16 v[58:61], v[166:169], v[190:193], v[58:61]
	v_mfma_f32_16x16x32_bf16 v[46:49], v[152:155], v[204:207], v[46:49]
	v_mfma_f32_16x16x32_bf16 v[42:45], v[166:169], v[204:207], v[42:45]
	v_mfma_f32_16x16x32_bf16 v[30:33], v[152:155], v[212:215], v[30:33]
	v_mfma_f32_16x16x32_bf16 v[26:29], v[166:169], v[212:215], v[26:29]
	v_mfma_f32_16x16x32_bf16 v[14:17], v[152:155], v[220:223], v[14:17]
	v_mfma_f32_16x16x32_bf16 v[10:13], v[166:169], v[220:223], v[10:13]
	v_mfma_f32_16x16x32_bf16 v[54:57], v[170:173], v[186:189], v[54:57]
	v_mfma_f32_16x16x32_bf16 v[50:53], v[178:181], v[186:189], v[50:53]
	v_mfma_f32_16x16x32_bf16 v[38:41], v[170:173], v[200:203], v[38:41]
	v_mfma_f32_16x16x32_bf16 v[34:37], v[178:181], v[200:203], v[34:37]
	v_mfma_f32_16x16x32_bf16 v[22:25], v[170:173], v[208:211], v[22:25]
	v_mfma_f32_16x16x32_bf16 v[18:21], v[178:181], v[208:211], v[18:21]
	v_mfma_f32_16x16x32_bf16 v[6:9], v[170:173], v[216:219], v[6:9]
	v_mfma_f32_16x16x32_bf16 v[2:5], v[178:181], v[216:219], v[2:5]
	v_mfma_f32_16x16x32_bf16 v[54:57], v[174:177], v[190:193], v[54:57]
	v_mfma_f32_16x16x32_bf16 v[50:53], v[182:185], v[190:193], v[50:53]
	v_mfma_f32_16x16x32_bf16 v[38:41], v[174:177], v[204:207], v[38:41]
	v_mfma_f32_16x16x32_bf16 v[34:37], v[182:185], v[204:207], v[34:37]
	v_mfma_f32_16x16x32_bf16 v[22:25], v[174:177], v[212:215], v[22:25]
	v_mfma_f32_16x16x32_bf16 v[18:21], v[182:185], v[212:215], v[18:21]
	v_mfma_f32_16x16x32_bf16 v[6:9], v[174:177], v[220:223], v[6:9]
	v_mfma_f32_16x16x32_bf16 v[2:5], v[182:185], v[220:223], v[2:5]
	s_barrier
	s_add_i32 s66, s66, 2
	s_add_u32 s0, s0, 0x100
	s_addc_u32 s1, s1, 0
	s_add_u32 s62, s62, 0x100
	s_addc_u32 s63, s63, 0
	s_cmp_gt_u32 s66, 29
	s_cbranch_scc0 .LBB0_762
	s_and_b64 vcc, exec, s[16:17]
	s_mov_b64 s[60:61], s[90:91]
	s_mov_b64 s[62:63], s[88:89]
	s_cbranch_vccz .LBB0_765
	s_barrier

; #define PG8_STAGE(bufoff, gbase, voff) do { _Pragma("unroll") for (int _i = 0; _i < 2; ++_i) \
;         __builtin_amdgcn_global_load_lds((const unsigned*)((const char*)(gbase) + (voff)[_i]), (PG8_LAS unsigned*)(lds + (bufoff) + ldsw + _i * 8192), 16, 0, 0); } while (0)
; #define PG8_LDA(dst, b, h) do { _Pragma("unroll") for (int m = 0; m < 4; ++m) _Pragma("unroll") for (int k = 0; k < 2; ++k) dst[m][k] = *(const PG8_LAS bf16x8*)(lds + PG8_SA(b, h) + aoff + m * 2048 + k * 1024); } while (0)
; #define PG8_LDB(dst, b, h) do { _Pragma("unroll") for (int n = 0; n < 2; ++n) _Pragma("unroll") for (int k = 0; k < 2; ++k) dst[n][k] = *(const PG8_LAS bf16x8*)(lds + PG8_SB(b, h) + boff + n * 2048 + k * 1024); } while (0)
; #define PG8_MMA(ai, bj, At, Bt) do { __builtin_amdgcn_s_setprio(1); _Pragma("unroll") for (int m = 0; m < 4; ++m) _Pragma("unroll") for (int n = 0; n < 2; ++n) _Pragma("unroll") for (int k = 0; k < 2; ++k) \
;         acc[ai][bj][m][n] = __builtin_amdgcn_mfma_f32_16x16x32_bf16(Bt[n][k], At[m][k], acc[ai][bj][m][n], 0, 0, 0); __builtin_amdgcn_s_setprio(0); } while (0)
; #define PG8_WAIT_V(n) asm volatile("s_waitcnt vmcnt(" #n ")" ::: "memory")
; #define PG8_WAIT_L(n) asm volatile("s_waitcnt lgkmcnt(" #n ")" ::: "memory")
; template <class Epi, class Sched, bool ALIGN_EPI = false, bool SP2 = false>
; __device__ __forceinline__ void gemm_phase(PG8_LAS unsigned char* lds, const Gemm g, const Sched& S, const Epi& E) {
;     ...
;             const bool last = (t == nt - 2);
;             const char* a1 = cA + (size_t)(t + 1) * kstep;
;             const char* a2 = last ? nA : cA + (size_t)(t + 2) * kstep; const char* b2 = last ? nB : cB + (size_t)(t + 2) * kstep;
;             const char* a3 = a2 + kstep; const char* b3 = b2 + kstep;
;             if (last && has_next) S.a_ready(nxt);
;             if constexpr (SP2) {
;             PG8_LDB(B0, 0, 0); PG8_LDB(B1, 0, 1); PG8_SCHED; PG8_LDA(At, 0, 0); PG8_STAGE(PG8_SA(1, 1), a1 + hstep, voffA);
;             PG8_WAIT_V(8); PG8_WAIT_L(0); PG8_BAR; PG8_MMA(0, 0, At, B0); PG8_MMA(0, 1, At, B1); PG8_BAR; PG8_SCHED;
;             PG8_LDA(At, 0, 1); PG8_STAGE(PG8_SB(0, 0), b2, voffB); PG8_STAGE(PG8_SB(0, 1), b2 + hstep, voffB); PG8_STAGE(PG8_SA(0, 0), a2, voffA);
;             PG8_WAIT_V(8); PG8_WAIT_L(0); PG8_BAR; PG8_MMA(1, 0, At, B0); PG8_MMA(1, 1, At, B1); PG8_BAR; PG8_SCHED;
.LBB0_842:
	s_add_u32 s30, s0, 0xffe00080
	s_addc_u32 s31, s1, -1
	s_add_i32 s68, 0, 0x10000
	s_cmpk_eq_i32 s67, 0x7c
	s_cselect_b32 s37, s23, s31
	s_cselect_b32 s36, s61, s30
	s_cselect_b32 s31, s19, s66
	s_cselect_b32 s30, s62, s63
	s_add_i32 s70, 0, 0x14000
	v_add_u32_e32 v142, s68, v199
	v_add_u32_e32 v162, s70, v199
	ds_read_b128 v[130:133], v142
	ds_read_b128 v[134:137], v142 offset:1024
	ds_read_b128 v[138:141], v142 offset:2048
	ds_read_b128 v[142:145], v142 offset:3072
	ds_read_b128 v[146:149], v162
	ds_read_b128 v[150:153], v162 offset:1024
	ds_read_b128 v[154:157], v162 offset:2048
	ds_read_b128 v[162:165], v162 offset:3072
	s_add_u32 s98, s0, 0xffe00000
	s_addc_u32 s99, s1, -1
	s_mov_b32 m0, s56
	s_nop 0
	global_load_lds_dwordx4 v172, s[98:99]
	s_mov_b32 m0, s57
	s_nop 0
	global_load_lds_dwordx4 v174, s[98:99]
	s_add_i32 m0, s51, 0xc000
	ds_read_b128 v[176:179], v201
	ds_read_b128 v[180:183], v201 offset:1024
	ds_read_b128 v[184:187], v201 offset:2048
	ds_read_b128 v[188:191], v201 offset:3072
	ds_read_b128 v[202:205], v201 offset:4096
	ds_read_b128 v[206:209], v201 offset:5120
	ds_read_b128 v[210:213], v201 offset:6144
	ds_read_b128 v[214:217], v201 offset:7168
	global_load_lds_dwordx4 v172, s[0:1]
	s_add_i32 m0, s51, 0xe000
	s_nop 0
	global_load_lds_dwordx4 v174, s[0:1]
	s_waitcnt vmcnt(8)
	s_waitcnt lgkmcnt(0)
	s_barrier
	v_mfma_f32_16x16x32_bf16 v[126:129], v[130:133], v[176:179], v[126:129]
	v_mfma_f32_16x16x32_bf16 v[122:125], v[138:141], v[176:179], v[122:125]
	v_mfma_f32_16x16x32_bf16 v[110:113], v[130:133], v[184:187], v[110:113]
	v_mfma_f32_16x16x32_bf16 v[106:109], v[138:141], v[184:187], v[106:109]
	v_mfma_f32_16x16x32_bf16 v[94:97], v[130:133], v[202:205], v[94:97]
	v_mfma_f32_16x16x32_bf16 v[90:93], v[138:141], v[202:205], v[90:93]
	v_mfma_f32_16x16x32_bf16 v[78:81], v[130:133], v[210:213], v[78:81]
	v_mfma_f32_16x16x32_bf16 v[74:77], v[138:141], v[210:213], v[74:77]
	v_mfma_f32_16x16x32_bf16 v[126:129], v[134:137], v[180:183], v[126:129]
	v_mfma_f32_16x16x32_bf16 v[122:125], v[142:145], v[180:183], v[122:125]
	v_mfma_f32_16x16x32_bf16 v[110:113], v[134:137], v[188:191], v[110:113]
	v_mfma_f32_16x16x32_bf16 v[106:109], v[142:145], v[188:191], v[106:109]
	v_mfma_f32_16x16x32_bf16 v[94:97], v[134:137], v[206:209], v[94:97]
	v_mfma_f32_16x16x32_bf16 v[90:93], v[142:145], v[206:209], v[90:93]
	v_mfma_f32_16x16x32_bf16 v[78:81], v[134:137], v[214:217], v[78:81]
	v_mfma_f32_16x16x32_bf16 v[74:77], v[142:145], v[214:217], v[74:77]
	v_mfma_f32_16x16x32_bf16 v[118:121], v[146:149], v[176:179], v[118:121]
	v_mfma_f32_16x16x32_bf16 v[114:117], v[154:157], v[176:179], v[114:117]
	v_mfma_f32_16x16x32_bf16 v[102:105], v[146:149], v[184:187], v[102:105]
	v_mfma_f32_16x16x32_bf16 v[98:101], v[154:157], v[184:187], v[98:101]
	v_mfma_f32_16x16x32_bf16 v[86:89], v[146:149], v[202:205], v[86:89]
	v_mfma_f32_16x16x32_bf16 v[82:85], v[154:157], v[202:205], v[82:85]
	v_mfma_f32_16x16x32_bf16 v[70:73], v[146:149], v[210:213], v[70:73]
	v_mfma_f32_16x16x32_bf16 v[66:69], v[154:157], v[210:213], v[66:69]
	v_mfma_f32_16x16x32_bf16 v[118:121], v[150:153], v[180:183], v[118:121]
	v_mfma_f32_16x16x32_bf16 v[114:117], v[162:165], v[180:183], v[114:117]
	v_mfma_f32_16x16x32_bf16 v[102:105], v[150:153], v[188:191], v[102:105]
	v_mfma_f32_16x16x32_bf16 v[98:101], v[162:165], v[188:191], v[98:101]
	v_mfma_f32_16x16x32_bf16 v[86:89], v[150:153], v[206:209], v[86:89]
	v_mfma_f32_16x16x32_bf16 v[82:85], v[162:165], v[206:209], v[82:85]
	v_mfma_f32_16x16x32_bf16 v[70:73], v[150:153], v[214:217], v[70:73]
	v_mfma_f32_16x16x32_bf16 v[66:69], v[162:165], v[214:217], v[66:69]
	s_barrier
	s_add_i32 s68, s68, s50
	s_mov_b32 m0, s68
	ds_read_b128 v[176:179], v201 offset:16384
	ds_read_b128 v[180:183], v201 offset:17408
	ds_read_b128 v[184:187], v201 offset:18432
	ds_read_b128 v[188:191], v201 offset:19456
	ds_read_b128 v[202:205], v201 offset:20480
	ds_read_b128 v[206:209], v201 offset:21504
	ds_read_b128 v[210:213], v201 offset:22528
	ds_read_b128 v[214:217], v201 offset:23552
	global_load_lds_dwordx4 v158, s[30:31]
	s_add_i32 m0, s68, 0x2000
	s_add_u32 s68, s30, 0x200000
	s_addc_u32 s69, s31, 0
	s_add_i32 s70, s70, s50
	global_load_lds_dwordx4 v166, s[30:31]
	s_mov_b32 m0, s70
	s_nop 0
	global_load_lds_dwordx4 v158, s[68:69]
	s_add_i32 m0, s70, 0x2000
	s_nop 0
	global_load_lds_dwordx4 v166, s[68:69]
	s_waitcnt vmcnt(6)
	s_waitcnt lgkmcnt(0)
	s_barrier
	v_mfma_f32_16x16x32_bf16 v[62:65], v[130:133], v[176:179], v[62:65]
	v_mfma_f32_16x16x32_bf16 v[58:61], v[138:141], v[176:179], v[58:61]
	v_mfma_f32_16x16x32_bf16 v[46:49], v[130:133], v[184:187], v[46:49]
	v_mfma_f32_16x16x32_bf16 v[42:45], v[138:141], v[184:187], v[42:45]
	v_mfma_f32_16x16x32_bf16 v[30:33], v[130:133], v[202:205], v[30:33]
	v_mfma_f32_16x16x32_bf16 v[26:29], v[138:141], v[202:205], v[26:29]
	v_mfma_f32_16x16x32_bf16 v[14:17], v[130:133], v[210:213], v[14:17]
	v_mfma_f32_16x16x32_bf16 v[10:13], v[138:141], v[210:213], v[10:13]
	v_mfma_f32_16x16x32_bf16 v[62:65], v[134:137], v[180:183], v[62:65]
	v_mfma_f32_16x16x32_bf16 v[58:61], v[142:145], v[180:183], v[58:61]
	v_mfma_f32_16x16x32_bf16 v[46:49], v[134:137], v[188:191], v[46:49]
	v_mfma_f32_16x16x32_bf16 v[42:45], v[142:145], v[188:191], v[42:45]
	v_mfma_f32_16x16x32_bf16 v[30:33], v[134:137], v[206:209], v[30:33]
	v_mfma_f32_16x16x32_bf16 v[26:29], v[142:145], v[206:209], v[26:29]
	v_mfma_f32_16x16x32_bf16 v[14:17], v[134:137], v[214:217], v[14:17]
	v_mfma_f32_16x16x32_bf16 v[10:13], v[142:145], v[214:217], v[10:13]
	v_mfma_f32_16x16x32_bf16 v[54:57], v[146:149], v[176:179], v[54:57]
	v_mfma_f32_16x16x32_bf16 v[50:53], v[154:157], v[176:179], v[50:53]
	v_mfma_f32_16x16x32_bf16 v[38:41], v[146:149], v[184:187], v[38:41]
	v_mfma_f32_16x16x32_bf16 v[34:37], v[154:157], v[184:187], v[34:37]
	v_mfma_f32_16x16x32_bf16 v[22:25], v[146:149], v[202:205], v[22:25]
	v_mfma_f32_16x16x32_bf16 v[18:21], v[154:157], v[202:205], v[18:21]
	v_mfma_f32_16x16x32_bf16 v[6:9], v[146:149], v[210:213], v[6:9]
	v_mfma_f32_16x16x32_bf16 v[2:5], v[154:157], v[210:213], v[2:5]
	v_mfma_f32_16x16x32_bf16 v[54:57], v[150:153], v[180:183], v[54:57]
	v_mfma_f32_16x16x32_bf16 v[50:53], v[162:165], v[180:183], v[50:53]
	v_mfma_f32_16x16x32_bf16 v[38:41], v[150:153], v[188:191], v[38:41]
	v_mfma_f32_16x16x32_bf16 v[34:37], v[162:165], v[188:191], v[34:37]
	v_mfma_f32_16x16x32_bf16 v[22:25], v[150:153], v[206:209], v[22:25]
	v_mfma_f32_16x16x32_bf16 v[18:21], v[162:165], v[206:209], v[18:21]
	v_mfma_f32_16x16x32_bf16 v[6:9], v[150:153], v[214:217], v[6:9]
	v_mfma_f32_16x16x32_bf16 v[2:5], v[162:165], v[214:217], v[2:5]
	s_barrier
; #define PG8_STAGE(bufoff, gbase, voff) do { _Pragma("unroll") for (int _i = 0; _i < 2; ++_i) \
;         __builtin_amdgcn_global_load_lds((const unsigned*)((const char*)(gbase) + (voff)[_i]), (PG8_LAS unsigned*)(lds + (bufoff) + ldsw + _i * 8192), 16, 0, 0); } while (0)
; #define PG8_LDA(dst, b, h) do { _Pragma("unroll") for (int m = 0; m < 4; ++m) _Pragma("unroll") for (int k = 0; k < 2; ++k) dst[m][k] = *(const PG8_LAS bf16x8*)(lds + PG8_SA(b, h) + aoff + m * 2048 + k * 1024); } while (0)
; #define PG8_LDB(dst, b, h) do { _Pragma("unroll") for (int n = 0; n < 2; ++n) _Pragma("unroll") for (int k = 0; k < 2; ++k) dst[n][k] = *(const PG8_LAS bf16x8*)(lds + PG8_SB(b, h) + boff + n * 2048 + k * 1024); } while (0)
; #define PG8_MMA(ai, bj, At, Bt) do { __builtin_amdgcn_s_setprio(1); _Pragma("unroll") for (int m = 0; m < 4; ++m) _Pragma("unroll") for (int n = 0; n < 2; ++n) _Pragma("unroll") for (int k = 0; k < 2; ++k) \
;         acc[ai][bj][m][n] = __builtin_amdgcn_mfma_f32_16x16x32_bf16(Bt[n][k], At[m][k], acc[ai][bj][m][n], 0, 0, 0); __builtin_amdgcn_s_setprio(0); } while (0)
; #define PG8_WAIT_V(n) asm volatile("s_waitcnt vmcnt(" #n ")" ::: "memory")
; #define PG8_WAIT_L(n) asm volatile("s_waitcnt lgkmcnt(" #n ")" ::: "memory")
; #define PG8_BAR __builtin_amdgcn_s_barrier()
; #define PG8_SCHED __builtin_amdgcn_sched_barrier(0)
; template <class Epi, class Sched, bool ALIGN_EPI = false, bool SP2 = false>
; __device__ __forceinline__ void gemm_phase(PG8_LAS unsigned char* lds, const Gemm g, const Sched& S, const Epi& E) {
;     ...
;             PG8_LDB(B0, 1, 0); PG8_LDB(B1, 1, 1); PG8_SCHED; PG8_LDA(At, 1, 0); PG8_STAGE(PG8_SA(0, 1), a2 + hstep, voffA);
;             PG8_WAIT_V(8); PG8_WAIT_L(0); PG8_BAR; PG8_MMA(0, 0, At, B0); PG8_MMA(0, 1, At, B1); PG8_BAR; PG8_SCHED;
;             PG8_LDA(At, 1, 1); PG8_STAGE(PG8_SB(1, 0), b3, voffB); PG8_STAGE(PG8_SB(1, 1), b3 + hstep, voffB); PG8_STAGE(PG8_SA(1, 0), a3, voffA);
;             PG8_WAIT_V(8); PG8_WAIT_L(0); PG8_BAR; PG8_MMA(1, 0, At, B0); PG8_MMA(1, 1, At, B1); PG8_BAR; PG8_SCHED;
	s_add_i32 s68, 0, 0x18000
	s_add_i32 s69, 0, 0x1c000
	v_add_u32_e32 v142, s68, v199
	v_add_u32_e32 v162, s69, v199
	ds_read_b128 v[130:133], v142
	ds_read_b128 v[134:137], v142 offset:1024
	ds_read_b128 v[138:141], v142 offset:2048
	ds_read_b128 v[142:145], v142 offset:3072
	ds_read_b128 v[146:149], v162
	ds_read_b128 v[150:153], v162 offset:1024
	ds_read_b128 v[154:157], v162 offset:2048
	ds_read_b128 v[162:165], v162 offset:3072
	s_mov_b32 m0, s51
	s_nop 0
	global_load_lds_dwordx4 v170, s[36:37]
	s_mov_b32 m0, s52
	s_nop 0
	global_load_lds_dwordx4 v168, s[36:37]
	s_add_u32 s36, s36, 0x200000
	s_addc_u32 s37, s37, 0
	s_mov_b32 m0, s53
	ds_read_b128 v[176:179], v201 offset:32768
	ds_read_b128 v[180:183], v201 offset:33792
	ds_read_b128 v[184:187], v201 offset:34816
	ds_read_b128 v[188:191], v201 offset:35840
	ds_read_b128 v[202:205], v201 offset:36864
	ds_read_b128 v[206:209], v201 offset:37888
	ds_read_b128 v[210:213], v201 offset:38912
	ds_read_b128 v[214:217], v201 offset:39936
	global_load_lds_dwordx4 v170, s[36:37]
	s_mov_b32 m0, s54
	s_nop 0
	global_load_lds_dwordx4 v168, s[36:37]
	s_waitcnt vmcnt(8)
	s_waitcnt lgkmcnt(0)
	s_barrier
	v_mfma_f32_16x16x32_bf16 v[126:129], v[130:133], v[176:179], v[126:129]
	v_mfma_f32_16x16x32_bf16 v[122:125], v[138:141], v[176:179], v[122:125]
	v_mfma_f32_16x16x32_bf16 v[110:113], v[130:133], v[184:187], v[110:113]
	v_mfma_f32_16x16x32_bf16 v[106:109], v[138:141], v[184:187], v[106:109]
	v_mfma_f32_16x16x32_bf16 v[94:97], v[130:133], v[202:205], v[94:97]
	v_mfma_f32_16x16x32_bf16 v[90:93], v[138:141], v[202:205], v[90:93]
	v_mfma_f32_16x16x32_bf16 v[78:81], v[130:133], v[210:213], v[78:81]
	v_mfma_f32_16x16x32_bf16 v[74:77], v[138:141], v[210:213], v[74:77]
	v_mfma_f32_16x16x32_bf16 v[126:129], v[134:137], v[180:183], v[126:129]
	v_mfma_f32_16x16x32_bf16 v[122:125], v[142:145], v[180:183], v[122:125]
	v_mfma_f32_16x16x32_bf16 v[110:113], v[134:137], v[188:191], v[110:113]
	v_mfma_f32_16x16x32_bf16 v[106:109], v[142:145], v[188:191], v[106:109]
	v_mfma_f32_16x16x32_bf16 v[94:97], v[134:137], v[206:209], v[94:97]
	v_mfma_f32_16x16x32_bf16 v[90:93], v[142:145], v[206:209], v[90:93]
	v_mfma_f32_16x16x32_bf16 v[78:81], v[134:137], v[214:217], v[78:81]
	v_mfma_f32_16x16x32_bf16 v[74:77], v[142:145], v[214:217], v[74:77]
	v_mfma_f32_16x16x32_bf16 v[118:121], v[146:149], v[176:179], v[118:121]
	v_mfma_f32_16x16x32_bf16 v[114:117], v[154:157], v[176:179], v[114:117]
	v_mfma_f32_16x16x32_bf16 v[102:105], v[146:149], v[184:187], v[102:105]
	v_mfma_f32_16x16x32_bf16 v[98:101], v[154:157], v[184:187], v[98:101]
	v_mfma_f32_16x16x32_bf16 v[86:89], v[146:149], v[202:205], v[86:89]
	v_mfma_f32_16x16x32_bf16 v[82:85], v[154:157], v[202:205], v[82:85]
	v_mfma_f32_16x16x32_bf16 v[70:73], v[146:149], v[210:213], v[70:73]
	v_mfma_f32_16x16x32_bf16 v[66:69], v[154:157], v[210:213], v[66:69]
	v_mfma_f32_16x16x32_bf16 v[118:121], v[150:153], v[180:183], v[118:121]
	v_mfma_f32_16x16x32_bf16 v[114:117], v[162:165], v[180:183], v[114:117]
	v_mfma_f32_16x16x32_bf16 v[102:105], v[150:153], v[188:191], v[102:105]
	v_mfma_f32_16x16x32_bf16 v[98:101], v[162:165], v[188:191], v[98:101]
	v_mfma_f32_16x16x32_bf16 v[86:89], v[150:153], v[206:209], v[86:89]
	v_mfma_f32_16x16x32_bf16 v[82:85], v[162:165], v[206:209], v[82:85]
	v_mfma_f32_16x16x32_bf16 v[70:73], v[150:153], v[214:217], v[70:73]
	v_mfma_f32_16x16x32_bf16 v[66:69], v[162:165], v[214:217], v[66:69]
	s_barrier
	s_add_i32 s36, s68, s50
	s_add_i32 m0, s36, 0xffffff80
	ds_read_b128 v[176:179], v201 offset:49152
	ds_read_b128 v[180:183], v201 offset:50176
	ds_read_b128 v[184:187], v201 offset:51200
	ds_read_b128 v[188:191], v201 offset:52224
	ds_read_b128 v[202:205], v201 offset:53248
	ds_read_b128 v[206:209], v201 offset:54272
	ds_read_b128 v[210:213], v201 offset:55296
	ds_read_b128 v[214:217], v201 offset:56320
	global_load_lds_dwordx4 v158, s[30:31] offset:128
	s_add_i32 m0, s36, 0x1f80
	s_add_i32 s36, s69, s50
	global_load_lds_dwordx4 v166, s[30:31] offset:128
	s_add_u32 s30, s30, 0x200080
	s_addc_u32 s31, s31, 0
	s_mov_b32 m0, s36
	s_nop 0
	global_load_lds_dwordx4 v158, s[30:31]
	s_add_i32 m0, s36, 0x2000
	s_nop 0
	global_load_lds_dwordx4 v166, s[30:31]
	s_waitcnt vmcnt(6)
	s_waitcnt lgkmcnt(0)
	s_barrier
	v_mfma_f32_16x16x32_bf16 v[62:65], v[130:133], v[176:179], v[62:65]
	v_mfma_f32_16x16x32_bf16 v[58:61], v[138:141], v[176:179], v[58:61]
	v_mfma_f32_16x16x32_bf16 v[46:49], v[130:133], v[184:187], v[46:49]
	v_mfma_f32_16x16x32_bf16 v[42:45], v[138:141], v[184:187], v[42:45]
	v_mfma_f32_16x16x32_bf16 v[30:33], v[130:133], v[202:205], v[30:33]
	v_mfma_f32_16x16x32_bf16 v[26:29], v[138:141], v[202:205], v[26:29]
	v_mfma_f32_16x16x32_bf16 v[14:17], v[130:133], v[210:213], v[14:17]
	v_mfma_f32_16x16x32_bf16 v[10:13], v[138:141], v[210:213], v[10:13]
	v_mfma_f32_16x16x32_bf16 v[62:65], v[134:137], v[180:183], v[62:65]
	v_mfma_f32_16x16x32_bf16 v[58:61], v[142:145], v[180:183], v[58:61]
	v_mfma_f32_16x16x32_bf16 v[46:49], v[134:137], v[188:191], v[46:49]
	v_mfma_f32_16x16x32_bf16 v[42:45], v[142:145], v[188:191], v[42:45]
	v_mfma_f32_16x16x32_bf16 v[30:33], v[134:137], v[206:209], v[30:33]
	v_mfma_f32_16x16x32_bf16 v[26:29], v[142:145], v[206:209], v[26:29]
	v_mfma_f32_16x16x32_bf16 v[14:17], v[134:137], v[214:217], v[14:17]
	v_mfma_f32_16x16x32_bf16 v[10:13], v[142:145], v[214:217], v[10:13]
	v_mfma_f32_16x16x32_bf16 v[54:57], v[146:149], v[176:179], v[54:57]
	v_mfma_f32_16x16x32_bf16 v[50:53], v[154:157], v[176:179], v[50:53]
	v_mfma_f32_16x16x32_bf16 v[38:41], v[146:149], v[184:187], v[38:41]
	v_mfma_f32_16x16x32_bf16 v[34:37], v[154:157], v[184:187], v[34:37]
	v_mfma_f32_16x16x32_bf16 v[22:25], v[146:149], v[202:205], v[22:25]
	v_mfma_f32_16x16x32_bf16 v[18:21], v[154:157], v[202:205], v[18:21]
	v_mfma_f32_16x16x32_bf16 v[6:9], v[146:149], v[210:213], v[6:9]
	v_mfma_f32_16x16x32_bf16 v[2:5], v[154:157], v[210:213], v[2:5]
	v_mfma_f32_16x16x32_bf16 v[54:57], v[150:153], v[180:183], v[54:57]
	v_mfma_f32_16x16x32_bf16 v[50:53], v[162:165], v[180:183], v[50:53]
	v_mfma_f32_16x16x32_bf16 v[38:41], v[150:153], v[188:191], v[38:41]
	v_mfma_f32_16x16x32_bf16 v[34:37], v[162:165], v[188:191], v[34:37]
	v_mfma_f32_16x16x32_bf16 v[22:25], v[150:153], v[206:209], v[22:25]
	v_mfma_f32_16x16x32_bf16 v[18:21], v[162:165], v[206:209], v[18:21]
	v_mfma_f32_16x16x32_bf16 v[6:9], v[150:153], v[214:217], v[6:9]
	v_mfma_f32_16x16x32_bf16 v[2:5], v[162:165], v[214:217], v[2:5]
	s_barrier
	s_add_i32 s67, s67, 2
	s_add_u32 s0, s0, 0x100
	s_addc_u32 s1, s1, 0
	s_add_u32 s63, s63, 0x100
	s_addc_u32 s66, s66, 0
	s_cmpk_gt_u32 s67, 0x7d
	s_cbranch_scc0 .LBB0_842
	s_and_b64 vcc, exec, s[16:17]
	s_cbranch_vccz .LBB0_845
	s_barrier

; #define PG8_STAGE(bufoff, gbase, voff) do { _Pragma("unroll") for (int _i = 0; _i < 2; ++_i) \
;         __builtin_amdgcn_global_load_lds((const unsigned*)((const char*)(gbase) + (voff)[_i]), (PG8_LAS unsigned*)(lds + (bufoff) + ldsw + _i * 8192), 16, 0, 0); } while (0)
; #define PG8_LDA(dst, b, h) do { _Pragma("unroll") for (int m = 0; m < 4; ++m) _Pragma("unroll") for (int k = 0; k < 2; ++k) dst[m][k] = *(const PG8_LAS bf16x8*)(lds + PG8_SA(b, h) + aoff + m * 2048 + k * 1024); } while (0)
; #define PG8_LDB(dst, b, h) do { _Pragma("unroll") for (int n = 0; n < 2; ++n) _Pragma("unroll") for (int k = 0; k < 2; ++k) dst[n][k] = *(const PG8_LAS bf16x8*)(lds + PG8_SB(b, h) + boff + n * 2048 + k * 1024); } while (0)
; #define PG8_MMA(ai, bj, At, Bt) do { __builtin_amdgcn_s_setprio(1); _Pragma("unroll") for (int m = 0; m < 4; ++m) _Pragma("unroll") for (int n = 0; n < 2; ++n) _Pragma("unroll") for (int k = 0; k < 2; ++k) \
;         acc[ai][bj][m][n] = __builtin_amdgcn_mfma_f32_16x16x32_bf16(Bt[n][k], At[m][k], acc[ai][bj][m][n], 0, 0, 0); __builtin_amdgcn_s_setprio(0); } while (0)
; #define PG8_WAIT_V(n) asm volatile("s_waitcnt vmcnt(" #n ")" ::: "memory")
; #define PG8_WAIT_L(n) asm volatile("s_waitcnt lgkmcnt(" #n ")" ::: "memory")
; template <class Epi, class Sched, bool ALIGN_EPI = false, bool SP2 = false>
; __device__ __forceinline__ void gemm_phase(PG8_LAS unsigned char* lds, const Gemm g, const Sched& S, const Epi& E) {
;     ...
;             const bool last = (t == nt - 2);
;             const char* a1 = cA + (size_t)(t + 1) * kstep;
;             const char* a2 = last ? nA : cA + (size_t)(t + 2) * kstep; const char* b2 = last ? nB : cB + (size_t)(t + 2) * kstep;
;             const char* a3 = a2 + kstep; const char* b3 = b2 + kstep;
;             if (last && has_next) S.a_ready(nxt);
;             if constexpr (SP2) {
;             PG8_LDB(B0, 0, 0); PG8_LDB(B1, 0, 1); PG8_SCHED; PG8_LDA(At, 0, 0); PG8_STAGE(PG8_SA(1, 1), a1 + hstep, voffA);
;             PG8_WAIT_V(8); PG8_WAIT_L(0); PG8_BAR; PG8_MMA(0, 0, At, B0); PG8_MMA(0, 1, At, B1); PG8_BAR; PG8_SCHED;
;             PG8_LDA(At, 0, 1); PG8_STAGE(PG8_SB(0, 0), b2, voffB); PG8_STAGE(PG8_SB(0, 1), b2 + hstep, voffB); PG8_STAGE(PG8_SA(0, 0), a2, voffA);
;             PG8_WAIT_V(8); PG8_WAIT_L(0); PG8_BAR; PG8_MMA(1, 0, At, B0); PG8_MMA(1, 1, At, B1); PG8_BAR; PG8_SCHED;
.LBB0_880:
	s_add_u32 s28, s0, 0xffe00080
	s_addc_u32 s29, s1, -1
	s_add_i32 s59, 0, 0x10000
	s_cmpk_eq_i32 s58, 0x7c
	s_cselect_b32 s31, s19, s29
	s_cselect_b32 s30, s54, s28
	s_cselect_b32 s29, s17, s57
	s_cselect_b32 s28, s55, s56
	s_add_i32 s62, 0, 0x14000
	v_add_u32_e32 v142, s59, v178
	v_add_u32_e32 v172, s62, v178
	ds_read_b128 v[130:133], v142
	ds_read_b128 v[134:137], v142 offset:1024
	ds_read_b128 v[138:141], v142 offset:2048
	ds_read_b128 v[142:145], v142 offset:3072
	ds_read_b128 v[146:149], v172
	ds_read_b128 v[162:165], v172 offset:1024
	ds_read_b128 v[168:171], v172 offset:2048
	ds_read_b128 v[172:175], v172 offset:3072
	s_add_u32 s98, s0, 0xffe00000
	s_addc_u32 s99, s1, -1
	s_mov_b32 m0, s44
	s_nop 0
	global_load_lds_dwordx4 v156, s[98:99]
	s_mov_b32 m0, s45
	s_nop 0
	global_load_lds_dwordx4 v166, s[98:99]
	s_add_i32 m0, s36, 0xc000
	ds_read_b128 v[182:185], v180
	ds_read_b128 v[186:189], v180 offset:1024
	ds_read_b128 v[190:193], v180 offset:2048
	ds_read_b128 v[200:203], v180 offset:3072
	ds_read_b128 v[204:207], v180 offset:4096
	ds_read_b128 v[208:211], v180 offset:5120
	ds_read_b128 v[212:215], v180 offset:6144
	ds_read_b128 v[216:219], v180 offset:7168
	global_load_lds_dwordx4 v156, s[0:1]
	s_add_i32 m0, s36, 0xe000
	s_nop 0
	global_load_lds_dwordx4 v166, s[0:1]
	s_waitcnt vmcnt(8)
	s_waitcnt lgkmcnt(0)
	s_barrier
	v_mfma_f32_16x16x32_bf16 v[126:129], v[130:133], v[182:185], v[126:129]
	v_mfma_f32_16x16x32_bf16 v[122:125], v[138:141], v[182:185], v[122:125]
	v_mfma_f32_16x16x32_bf16 v[118:121], v[130:133], v[190:193], v[118:121]
	v_mfma_f32_16x16x32_bf16 v[114:117], v[138:141], v[190:193], v[114:117]
	v_mfma_f32_16x16x32_bf16 v[94:97], v[130:133], v[204:207], v[94:97]
	v_mfma_f32_16x16x32_bf16 v[90:93], v[138:141], v[204:207], v[90:93]
	v_mfma_f32_16x16x32_bf16 v[82:85], v[130:133], v[212:215], v[82:85]
	v_mfma_f32_16x16x32_bf16 v[74:77], v[138:141], v[212:215], v[74:77]
	v_mfma_f32_16x16x32_bf16 v[126:129], v[134:137], v[186:189], v[126:129]
	v_mfma_f32_16x16x32_bf16 v[122:125], v[142:145], v[186:189], v[122:125]
	v_mfma_f32_16x16x32_bf16 v[118:121], v[134:137], v[200:203], v[118:121]
	v_mfma_f32_16x16x32_bf16 v[114:117], v[142:145], v[200:203], v[114:117]
	v_mfma_f32_16x16x32_bf16 v[94:97], v[134:137], v[208:211], v[94:97]
	v_mfma_f32_16x16x32_bf16 v[90:93], v[142:145], v[208:211], v[90:93]
	v_mfma_f32_16x16x32_bf16 v[82:85], v[134:137], v[216:219], v[82:85]
	v_mfma_f32_16x16x32_bf16 v[74:77], v[142:145], v[216:219], v[74:77]
	v_mfma_f32_16x16x32_bf16 v[110:113], v[146:149], v[182:185], v[110:113]
	v_mfma_f32_16x16x32_bf16 v[106:109], v[168:171], v[182:185], v[106:109]
	v_mfma_f32_16x16x32_bf16 v[102:105], v[146:149], v[190:193], v[102:105]
	v_mfma_f32_16x16x32_bf16 v[98:101], v[168:171], v[190:193], v[98:101]
	v_mfma_f32_16x16x32_bf16 v[86:89], v[146:149], v[204:207], v[86:89]
	v_mfma_f32_16x16x32_bf16 v[78:81], v[168:171], v[204:207], v[78:81]
	v_mfma_f32_16x16x32_bf16 v[70:73], v[146:149], v[212:215], v[70:73]
	v_mfma_f32_16x16x32_bf16 v[66:69], v[168:171], v[212:215], v[66:69]
	v_mfma_f32_16x16x32_bf16 v[110:113], v[162:165], v[186:189], v[110:113]
	v_mfma_f32_16x16x32_bf16 v[106:109], v[172:175], v[186:189], v[106:109]
	v_mfma_f32_16x16x32_bf16 v[102:105], v[162:165], v[200:203], v[102:105]
	v_mfma_f32_16x16x32_bf16 v[98:101], v[172:175], v[200:203], v[98:101]
	v_mfma_f32_16x16x32_bf16 v[86:89], v[162:165], v[208:211], v[86:89]
	v_mfma_f32_16x16x32_bf16 v[78:81], v[172:175], v[208:211], v[78:81]
	v_mfma_f32_16x16x32_bf16 v[70:73], v[162:165], v[216:219], v[70:73]
	v_mfma_f32_16x16x32_bf16 v[66:69], v[172:175], v[216:219], v[66:69]
	s_barrier
	s_add_i32 s59, s59, s34
	s_mov_b32 m0, s59
	ds_read_b128 v[182:185], v180 offset:16384
	ds_read_b128 v[186:189], v180 offset:17408
	ds_read_b128 v[190:193], v180 offset:18432
	ds_read_b128 v[200:203], v180 offset:19456
	ds_read_b128 v[204:207], v180 offset:20480
	ds_read_b128 v[208:211], v180 offset:21504
	ds_read_b128 v[212:215], v180 offset:22528
	ds_read_b128 v[216:219], v180 offset:23552
	global_load_lds_dwordx4 v158, s[28:29]
	s_add_i32 m0, s59, 0x2000
	s_add_u32 s60, s28, 0x200000
	s_addc_u32 s61, s29, 0
	s_add_i32 s59, s62, s34
	global_load_lds_dwordx4 v150, s[28:29]
	s_mov_b32 m0, s59
	s_nop 0
	global_load_lds_dwordx4 v158, s[60:61]
	s_add_i32 m0, s59, 0x2000
	s_nop 0
	global_load_lds_dwordx4 v150, s[60:61]
	s_waitcnt vmcnt(6)
	s_waitcnt lgkmcnt(0)
	s_barrier
	v_mfma_f32_16x16x32_bf16 v[62:65], v[130:133], v[182:185], v[62:65]
	v_mfma_f32_16x16x32_bf16 v[58:61], v[138:141], v[182:185], v[58:61]
	v_mfma_f32_16x16x32_bf16 v[50:53], v[130:133], v[190:193], v[50:53]
	v_mfma_f32_16x16x32_bf16 v[42:45], v[138:141], v[190:193], v[42:45]
	v_mfma_f32_16x16x32_bf16 v[34:37], v[130:133], v[204:207], v[34:37]
	v_mfma_f32_16x16x32_bf16 v[26:29], v[138:141], v[204:207], v[26:29]
	v_mfma_f32_16x16x32_bf16 v[18:21], v[130:133], v[212:215], v[18:21]
	v_mfma_f32_16x16x32_bf16 v[10:13], v[138:141], v[212:215], v[10:13]
	v_mfma_f32_16x16x32_bf16 v[62:65], v[134:137], v[186:189], v[62:65]
	v_mfma_f32_16x16x32_bf16 v[58:61], v[142:145], v[186:189], v[58:61]
	v_mfma_f32_16x16x32_bf16 v[50:53], v[134:137], v[200:203], v[50:53]
	v_mfma_f32_16x16x32_bf16 v[42:45], v[142:145], v[200:203], v[42:45]
	v_mfma_f32_16x16x32_bf16 v[34:37], v[134:137], v[208:211], v[34:37]
	v_mfma_f32_16x16x32_bf16 v[26:29], v[142:145], v[208:211], v[26:29]
	v_mfma_f32_16x16x32_bf16 v[18:21], v[134:137], v[216:219], v[18:21]
	v_mfma_f32_16x16x32_bf16 v[10:13], v[142:145], v[216:219], v[10:13]
	v_mfma_f32_16x16x32_bf16 v[54:57], v[146:149], v[182:185], v[54:57]
	v_mfma_f32_16x16x32_bf16 v[46:49], v[168:171], v[182:185], v[46:49]
	v_mfma_f32_16x16x32_bf16 v[38:41], v[146:149], v[190:193], v[38:41]
	v_mfma_f32_16x16x32_bf16 v[30:33], v[168:171], v[190:193], v[30:33]
	v_mfma_f32_16x16x32_bf16 v[22:25], v[146:149], v[204:207], v[22:25]
	v_mfma_f32_16x16x32_bf16 v[14:17], v[168:171], v[204:207], v[14:17]
	v_mfma_f32_16x16x32_bf16 v[6:9], v[146:149], v[212:215], v[6:9]
	v_mfma_f32_16x16x32_bf16 v[2:5], v[168:171], v[212:215], v[2:5]
	v_mfma_f32_16x16x32_bf16 v[54:57], v[162:165], v[186:189], v[54:57]
	v_mfma_f32_16x16x32_bf16 v[46:49], v[172:175], v[186:189], v[46:49]
	v_mfma_f32_16x16x32_bf16 v[38:41], v[162:165], v[200:203], v[38:41]
	v_mfma_f32_16x16x32_bf16 v[30:33], v[172:175], v[200:203], v[30:33]
	v_mfma_f32_16x16x32_bf16 v[22:25], v[162:165], v[208:211], v[22:25]
	v_mfma_f32_16x16x32_bf16 v[14:17], v[172:175], v[208:211], v[14:17]
	v_mfma_f32_16x16x32_bf16 v[6:9], v[162:165], v[216:219], v[6:9]
	v_mfma_f32_16x16x32_bf16 v[2:5], v[172:175], v[216:219], v[2:5]
	s_barrier
; #define PG8_STAGE(bufoff, gbase, voff) do { _Pragma("unroll") for (int _i = 0; _i < 2; ++_i) \
;         __builtin_amdgcn_global_load_lds((const unsigned*)((const char*)(gbase) + (voff)[_i]), (PG8_LAS unsigned*)(lds + (bufoff) + ldsw + _i * 8192), 16, 0, 0); } while (0)
; #define PG8_LDA(dst, b, h) do { _Pragma("unroll") for (int m = 0; m < 4; ++m) _Pragma("unroll") for (int k = 0; k < 2; ++k) dst[m][k] = *(const PG8_LAS bf16x8*)(lds + PG8_SA(b, h) + aoff + m * 2048 + k * 1024); } while (0)
; #define PG8_LDB(dst, b, h) do { _Pragma("unroll") for (int n = 0; n < 2; ++n) _Pragma("unroll") for (int k = 0; k < 2; ++k) dst[n][k] = *(const PG8_LAS bf16x8*)(lds + PG8_SB(b, h) + boff + n * 2048 + k * 1024); } while (0)
; #define PG8_MMA(ai, bj, At, Bt) do { __builtin_amdgcn_s_setprio(1); _Pragma("unroll") for (int m = 0; m < 4; ++m) _Pragma("unroll") for (int n = 0; n < 2; ++n) _Pragma("unroll") for (int k = 0; k < 2; ++k) \
;         acc[ai][bj][m][n] = __builtin_amdgcn_mfma_f32_16x16x32_bf16(Bt[n][k], At[m][k], acc[ai][bj][m][n], 0, 0, 0); __builtin_amdgcn_s_setprio(0); } while (0)
; #define PG8_WAIT_V(n) asm volatile("s_waitcnt vmcnt(" #n ")" ::: "memory")
; #define PG8_WAIT_L(n) asm volatile("s_waitcnt lgkmcnt(" #n ")" ::: "memory")
; #define PG8_BAR __builtin_amdgcn_s_barrier()
; #define PG8_SCHED __builtin_amdgcn_sched_barrier(0)
; template <class Epi, class Sched, bool ALIGN_EPI = false, bool SP2 = false>
; __device__ __forceinline__ void gemm_phase(PG8_LAS unsigned char* lds, const Gemm g, const Sched& S, const Epi& E) {
;     ...
;             PG8_LDB(B0, 1, 0); PG8_LDB(B1, 1, 1); PG8_SCHED; PG8_LDA(At, 1, 0); PG8_STAGE(PG8_SA(0, 1), a2 + hstep, voffA);
;             PG8_WAIT_V(8); PG8_WAIT_L(0); PG8_BAR; PG8_MMA(0, 0, At, B0); PG8_MMA(0, 1, At, B1); PG8_BAR; PG8_SCHED;
;             PG8_LDA(At, 1, 1); PG8_STAGE(PG8_SB(1, 0), b3, voffB); PG8_STAGE(PG8_SB(1, 1), b3 + hstep, voffB); PG8_STAGE(PG8_SA(1, 0), a3, voffA);
;             PG8_WAIT_V(8); PG8_WAIT_L(0); PG8_BAR; PG8_MMA(1, 0, At, B0); PG8_MMA(1, 1, At, B1); PG8_BAR; PG8_SCHED;
	s_add_i32 s59, 0, 0x18000
	s_add_i32 s60, 0, 0x1c000
	v_add_u32_e32 v142, s59, v178
	v_add_u32_e32 v172, s60, v178
	ds_read_b128 v[130:133], v142
	ds_read_b128 v[134:137], v142 offset:1024
	ds_read_b128 v[138:141], v142 offset:2048
	ds_read_b128 v[142:145], v142 offset:3072
	ds_read_b128 v[146:149], v172
	ds_read_b128 v[162:165], v172 offset:1024
	ds_read_b128 v[168:171], v172 offset:2048
	ds_read_b128 v[172:175], v172 offset:3072
	s_mov_b32 m0, s36
	s_nop 0
	global_load_lds_dwordx4 v154, s[30:31]
	s_mov_b32 m0, s37
	s_nop 0
	global_load_lds_dwordx4 v152, s[30:31]
	s_add_u32 s30, s30, 0x200000
	s_addc_u32 s31, s31, 0
	s_mov_b32 m0, s42
	ds_read_b128 v[182:185], v180 offset:32768
	ds_read_b128 v[186:189], v180 offset:33792
	ds_read_b128 v[190:193], v180 offset:34816
	ds_read_b128 v[200:203], v180 offset:35840
	ds_read_b128 v[204:207], v180 offset:36864
	ds_read_b128 v[208:211], v180 offset:37888
	ds_read_b128 v[212:215], v180 offset:38912
	ds_read_b128 v[216:219], v180 offset:39936
	global_load_lds_dwordx4 v154, s[30:31]
	s_mov_b32 m0, s43
	s_nop 0
	global_load_lds_dwordx4 v152, s[30:31]
	s_waitcnt vmcnt(8)
	s_waitcnt lgkmcnt(0)
	s_barrier
	v_mfma_f32_16x16x32_bf16 v[126:129], v[130:133], v[182:185], v[126:129]
	v_mfma_f32_16x16x32_bf16 v[122:125], v[138:141], v[182:185], v[122:125]
	v_mfma_f32_16x16x32_bf16 v[118:121], v[130:133], v[190:193], v[118:121]
	v_mfma_f32_16x16x32_bf16 v[114:117], v[138:141], v[190:193], v[114:117]
	v_mfma_f32_16x16x32_bf16 v[94:97], v[130:133], v[204:207], v[94:97]
	v_mfma_f32_16x16x32_bf16 v[90:93], v[138:141], v[204:207], v[90:93]
	v_mfma_f32_16x16x32_bf16 v[82:85], v[130:133], v[212:215], v[82:85]
	v_mfma_f32_16x16x32_bf16 v[74:77], v[138:141], v[212:215], v[74:77]
	v_mfma_f32_16x16x32_bf16 v[126:129], v[134:137], v[186:189], v[126:129]
	v_mfma_f32_16x16x32_bf16 v[122:125], v[142:145], v[186:189], v[122:125]
	v_mfma_f32_16x16x32_bf16 v[118:121], v[134:137], v[200:203], v[118:121]
	v_mfma_f32_16x16x32_bf16 v[114:117], v[142:145], v[200:203], v[114:117]
	v_mfma_f32_16x16x32_bf16 v[94:97], v[134:137], v[208:211], v[94:97]
	v_mfma_f32_16x16x32_bf16 v[90:93], v[142:145], v[208:211], v[90:93]
	v_mfma_f32_16x16x32_bf16 v[82:85], v[134:137], v[216:219], v[82:85]
	v_mfma_f32_16x16x32_bf16 v[74:77], v[142:145], v[216:219], v[74:77]
	v_mfma_f32_16x16x32_bf16 v[110:113], v[146:149], v[182:185], v[110:113]
	v_mfma_f32_16x16x32_bf16 v[106:109], v[168:171], v[182:185], v[106:109]
	v_mfma_f32_16x16x32_bf16 v[102:105], v[146:149], v[190:193], v[102:105]
	v_mfma_f32_16x16x32_bf16 v[98:101], v[168:171], v[190:193], v[98:101]
	v_mfma_f32_16x16x32_bf16 v[86:89], v[146:149], v[204:207], v[86:89]
	v_mfma_f32_16x16x32_bf16 v[78:81], v[168:171], v[204:207], v[78:81]
	v_mfma_f32_16x16x32_bf16 v[70:73], v[146:149], v[212:215], v[70:73]
	v_mfma_f32_16x16x32_bf16 v[66:69], v[168:171], v[212:215], v[66:69]
	v_mfma_f32_16x16x32_bf16 v[110:113], v[162:165], v[186:189], v[110:113]
	v_mfma_f32_16x16x32_bf16 v[106:109], v[172:175], v[186:189], v[106:109]
	v_mfma_f32_16x16x32_bf16 v[102:105], v[162:165], v[200:203], v[102:105]
	v_mfma_f32_16x16x32_bf16 v[98:101], v[172:175], v[200:203], v[98:101]
	v_mfma_f32_16x16x32_bf16 v[86:89], v[162:165], v[208:211], v[86:89]
	v_mfma_f32_16x16x32_bf16 v[78:81], v[172:175], v[208:211], v[78:81]
	v_mfma_f32_16x16x32_bf16 v[70:73], v[162:165], v[216:219], v[70:73]
	v_mfma_f32_16x16x32_bf16 v[66:69], v[172:175], v[216:219], v[66:69]
	s_barrier
	s_add_i32 s30, s59, s34
	s_add_i32 m0, s30, 0xffffff80
	ds_read_b128 v[182:185], v180 offset:49152
	ds_read_b128 v[186:189], v180 offset:50176
	ds_read_b128 v[190:193], v180 offset:51200
	ds_read_b128 v[200:203], v180 offset:52224
	ds_read_b128 v[204:207], v180 offset:53248
	ds_read_b128 v[208:211], v180 offset:54272
	ds_read_b128 v[212:215], v180 offset:55296
	ds_read_b128 v[216:219], v180 offset:56320
	global_load_lds_dwordx4 v158, s[28:29] offset:128
	s_add_i32 m0, s30, 0x1f80
	s_add_i32 s30, s60, s34
	global_load_lds_dwordx4 v150, s[28:29] offset:128
	s_add_u32 s28, s28, 0x200080
	s_addc_u32 s29, s29, 0
	s_mov_b32 m0, s30
	s_nop 0
	global_load_lds_dwordx4 v158, s[28:29]
	s_add_i32 m0, s30, 0x2000
	s_nop 0
	global_load_lds_dwordx4 v150, s[28:29]
	s_waitcnt vmcnt(6)
	s_waitcnt lgkmcnt(0)
	s_barrier
	v_mfma_f32_16x16x32_bf16 v[62:65], v[130:133], v[182:185], v[62:65]
	v_mfma_f32_16x16x32_bf16 v[58:61], v[138:141], v[182:185], v[58:61]
	v_mfma_f32_16x16x32_bf16 v[50:53], v[130:133], v[190:193], v[50:53]
	v_mfma_f32_16x16x32_bf16 v[42:45], v[138:141], v[190:193], v[42:45]
	v_mfma_f32_16x16x32_bf16 v[34:37], v[130:133], v[204:207], v[34:37]
	v_mfma_f32_16x16x32_bf16 v[26:29], v[138:141], v[204:207], v[26:29]
	v_mfma_f32_16x16x32_bf16 v[18:21], v[130:133], v[212:215], v[18:21]
	v_mfma_f32_16x16x32_bf16 v[10:13], v[138:141], v[212:215], v[10:13]
	v_mfma_f32_16x16x32_bf16 v[62:65], v[134:137], v[186:189], v[62:65]
	v_mfma_f32_16x16x32_bf16 v[58:61], v[142:145], v[186:189], v[58:61]
	v_mfma_f32_16x16x32_bf16 v[50:53], v[134:137], v[200:203], v[50:53]
	v_mfma_f32_16x16x32_bf16 v[42:45], v[142:145], v[200:203], v[42:45]
	v_mfma_f32_16x16x32_bf16 v[34:37], v[134:137], v[208:211], v[34:37]
	v_mfma_f32_16x16x32_bf16 v[26:29], v[142:145], v[208:211], v[26:29]
	v_mfma_f32_16x16x32_bf16 v[18:21], v[134:137], v[216:219], v[18:21]
	v_mfma_f32_16x16x32_bf16 v[10:13], v[142:145], v[216:219], v[10:13]
	v_mfma_f32_16x16x32_bf16 v[54:57], v[146:149], v[182:185], v[54:57]
	v_mfma_f32_16x16x32_bf16 v[46:49], v[168:171], v[182:185], v[46:49]
	v_mfma_f32_16x16x32_bf16 v[38:41], v[146:149], v[190:193], v[38:41]
	v_mfma_f32_16x16x32_bf16 v[30:33], v[168:171], v[190:193], v[30:33]
	v_mfma_f32_16x16x32_bf16 v[22:25], v[146:149], v[204:207], v[22:25]
	v_mfma_f32_16x16x32_bf16 v[14:17], v[168:171], v[204:207], v[14:17]
	v_mfma_f32_16x16x32_bf16 v[6:9], v[146:149], v[212:215], v[6:9]
	v_mfma_f32_16x16x32_bf16 v[2:5], v[168:171], v[212:215], v[2:5]
	v_mfma_f32_16x16x32_bf16 v[54:57], v[162:165], v[186:189], v[54:57]
	v_mfma_f32_16x16x32_bf16 v[46:49], v[172:175], v[186:189], v[46:49]
	v_mfma_f32_16x16x32_bf16 v[38:41], v[162:165], v[200:203], v[38:41]
	v_mfma_f32_16x16x32_bf16 v[30:33], v[172:175], v[200:203], v[30:33]
	v_mfma_f32_16x16x32_bf16 v[22:25], v[162:165], v[208:211], v[22:25]
	v_mfma_f32_16x16x32_bf16 v[14:17], v[172:175], v[208:211], v[14:17]
	v_mfma_f32_16x16x32_bf16 v[6:9], v[162:165], v[216:219], v[6:9]
	v_mfma_f32_16x16x32_bf16 v[2:5], v[172:175], v[216:219], v[2:5]
	s_barrier
	s_add_i32 s58, s58, 2
	s_add_u32 s0, s0, 0x100
	s_addc_u32 s1, s1, 0
	s_add_u32 s56, s56, 0x100
	s_addc_u32 s57, s57, 0
	s_cmpk_gt_u32 s58, 0x7d
	s_cbranch_scc0 .LBB0_880
	s_and_b64 vcc, exec, s[14:15]
	s_cbranch_vccz .LBB0_883
	s_barrier
